# ordering check: second MMA block (bj=1) issued before the first inside each super-phase
# baseline (speedup 1.0000x reference)
; #define PG8_STAGE(bufoff, gbase, voff) do { _Pragma("unroll") for (int _i = 0; _i < 2; ++_i) \
;         __builtin_amdgcn_global_load_lds((const unsigned*)((const char*)(gbase) + (voff)[_i]), (PG8_LAS unsigned*)(lds + (bufoff) + ldsw + _i * 8192), 16, 0, 0); } while (0)
; #define PG8_LDA(dst, b, h) do { _Pragma("unroll") for (int m = 0; m < 4; ++m) _Pragma("unroll") for (int k = 0; k < 2; ++k) dst[m][k] = *(const PG8_LAS bf16x8*)(lds + PG8_SA(b, h) + aoff + m * 2048 + k * 1024); } while (0)
; #define PG8_LDB(dst, b, h) do { _Pragma("unroll") for (int n = 0; n < 2; ++n) _Pragma("unroll") for (int k = 0; k < 2; ++k) dst[n][k] = *(const PG8_LAS bf16x8*)(lds + PG8_SB(b, h) + boff + n * 2048 + k * 1024); } while (0)
; #define PG8_MMA(ai, bj, At, Bt) do { __builtin_amdgcn_s_setprio(1); _Pragma("unroll") for (int m = 0; m < 4; ++m) _Pragma("unroll") for (int n = 0; n < 2; ++n) _Pragma("unroll") for (int k = 0; k < 2; ++k) \
;         acc[ai][bj][m][n] = __builtin_amdgcn_mfma_f32_16x16x32_bf16(Bt[n][k], At[m][k], acc[ai][bj][m][n], 0, 0, 0); __builtin_amdgcn_s_setprio(0); } while (0)
; #define PG8_WAIT_V(n) asm volatile("s_waitcnt vmcnt(" #n ")" ::: "memory")
; #define PG8_WAIT_L(n) asm volatile("s_waitcnt lgkmcnt(" #n ")" ::: "memory")
; template <class Epi, class Sched, bool ALIGN_EPI = false, bool SP2 = false>
; __device__ __forceinline__ void gemm_phase(PG8_LAS unsigned char* lds, const Gemm g, const Sched& S, const Epi& E) {
;     ...
;             const bool last = (t == nt - 2);
;             const char* a1 = cA + (size_t)(t + 1) * kstep;
;             const char* a2 = last ? nA : cA + (size_t)(t + 2) * kstep; const char* b2 = last ? nB : cB + (size_t)(t + 2) * kstep;
;             const char* a3 = a2 + kstep; const char* b3 = b2 + kstep;
;             if (last && has_next) S.a_ready(nxt);
;             if constexpr (SP2) {
;             PG8_LDB(B0, 0, 0); PG8_LDB(B1, 0, 1); PG8_SCHED; PG8_LDA(At, 0, 0); PG8_STAGE(PG8_SA(1, 1), a1 + hstep, voffA);
;             PG8_WAIT_V(8); PG8_WAIT_L(0); PG8_BAR; PG8_MMA(0, 0, At, B0); PG8_MMA(0, 1, At, B1); PG8_BAR; PG8_SCHED;
;             PG8_LDA(At, 0, 1); PG8_STAGE(PG8_SB(0, 0), b2, voffB); PG8_STAGE(PG8_SB(0, 1), b2 + hstep, voffB); PG8_STAGE(PG8_SA(0, 0), a2, voffA);
;             PG8_WAIT_V(8); PG8_WAIT_L(0); PG8_BAR; PG8_MMA(1, 0, At, B0); PG8_MMA(1, 1, At, B1); PG8_BAR; PG8_SCHED;
.LBB0_132:
	s_add_u32 s18, s46, 0xfffc0080
	s_addc_u32 s38, s47, -1
	s_add_i32 s39, 0, 0x10000
	s_cmp_eq_u32 s85, 12
	s_cselect_b32 s81, s33, s38
	s_cselect_b32 s80, s73, s18
	v_add_u32_e32 v0, s39, v176
	s_cselect_b32 s45, s75, s84
	s_cselect_b32 s44, s82, s83
	s_add_i32 s18, 0, 0x14000
	ds_read_b128 v[144:147], v0
	ds_read_b128 v[148:151], v0 offset:1024
	ds_read_b128 v[152:155], v0 offset:2048
	ds_read_b128 v[156:159], v0 offset:3072
	v_add_u32_e32 v0, s18, v176
	ds_read_b128 v[160:163], v0
	ds_read_b128 v[164:167], v0 offset:1024
	ds_read_b128 v[168:171], v0 offset:2048
	ds_read_b128 v[172:175], v0 offset:3072
	v_lshl_add_u64 v[218:219], s[46:47], 0, v[140:141]
	s_add_i32 m0, s92, 0xc000
	ds_read_b128 v[180:183], v178
	ds_read_b128 v[184:187], v178 offset:1024
	ds_read_b128 v[188:191], v178 offset:2048
	ds_read_b128 v[192:195], v178 offset:3072
	ds_read_b128 v[202:205], v178 offset:4096
	ds_read_b128 v[206:209], v178 offset:5120
	ds_read_b128 v[210:213], v178 offset:6144
	ds_read_b128 v[214:217], v178 offset:7168
	global_load_lds_dwordx4 v[218:219], off
	v_lshl_add_u64 v[218:219], s[46:47], 0, v[142:143]
	s_add_i32 m0, s92, 0xe000
	s_nop 0
	global_load_lds_dwordx4 v[218:219], off
	s_waitcnt vmcnt(8)
	s_waitcnt lgkmcnt(0)
	s_barrier
	s_setprio 1
	v_mfma_f32_16x16x32_bf16 v[126:129], v[160:163], v[180:183], v[126:129]
	v_mfma_f32_16x16x32_bf16 v[126:129], v[164:167], v[184:187], v[126:129]
	v_mfma_f32_16x16x32_bf16 v[110:113], v[160:163], v[188:191], v[110:113]
	v_mfma_f32_16x16x32_bf16 v[110:113], v[164:167], v[192:195], v[110:113]
	v_mfma_f32_16x16x32_bf16 v[94:97], v[160:163], v[202:205], v[94:97]
	v_mfma_f32_16x16x32_bf16 v[94:97], v[164:167], v[206:209], v[94:97]
	v_mfma_f32_16x16x32_bf16 v[78:81], v[160:163], v[210:213], v[78:81]
	v_mfma_f32_16x16x32_bf16 v[78:81], v[164:167], v[214:217], v[78:81]
	v_mfma_f32_16x16x32_bf16 v[122:125], v[168:171], v[180:183], v[122:125]
	v_mfma_f32_16x16x32_bf16 v[122:125], v[172:175], v[184:187], v[122:125]
	v_mfma_f32_16x16x32_bf16 v[106:109], v[168:171], v[188:191], v[106:109]
	v_mfma_f32_16x16x32_bf16 v[106:109], v[172:175], v[192:195], v[106:109]
	v_mfma_f32_16x16x32_bf16 v[90:93], v[168:171], v[202:205], v[90:93]
	v_mfma_f32_16x16x32_bf16 v[90:93], v[172:175], v[206:209], v[90:93]
	v_mfma_f32_16x16x32_bf16 v[74:77], v[168:171], v[210:213], v[74:77]
	v_mfma_f32_16x16x32_bf16 v[74:77], v[172:175], v[214:217], v[74:77]
	v_mfma_f32_16x16x32_bf16 v[118:121], v[144:147], v[180:183], v[118:121]
	v_mfma_f32_16x16x32_bf16 v[118:121], v[148:151], v[184:187], v[118:121]
	v_mfma_f32_16x16x32_bf16 v[102:105], v[144:147], v[188:191], v[102:105]
	v_mfma_f32_16x16x32_bf16 v[102:105], v[148:151], v[192:195], v[102:105]
	v_mfma_f32_16x16x32_bf16 v[86:89], v[144:147], v[202:205], v[86:89]
	v_mfma_f32_16x16x32_bf16 v[86:89], v[148:151], v[206:209], v[86:89]
	v_mfma_f32_16x16x32_bf16 v[70:73], v[144:147], v[210:213], v[70:73]
	v_mfma_f32_16x16x32_bf16 v[70:73], v[148:151], v[214:217], v[70:73]
	v_mfma_f32_16x16x32_bf16 v[114:117], v[152:155], v[180:183], v[114:117]
	v_mfma_f32_16x16x32_bf16 v[114:117], v[156:159], v[184:187], v[114:117]
	v_mfma_f32_16x16x32_bf16 v[98:101], v[152:155], v[188:191], v[98:101]
	v_mfma_f32_16x16x32_bf16 v[98:101], v[156:159], v[192:195], v[98:101]
	v_mfma_f32_16x16x32_bf16 v[82:85], v[152:155], v[202:205], v[82:85]
	v_mfma_f32_16x16x32_bf16 v[82:85], v[156:159], v[206:209], v[82:85]
	v_mfma_f32_16x16x32_bf16 v[66:69], v[152:155], v[210:213], v[66:69]
	v_mfma_f32_16x16x32_bf16 v[66:69], v[156:159], v[214:217], v[66:69]
	s_setprio 0
	s_barrier
	s_add_i32 s38, s39, s91
	v_lshl_add_u64 v[218:219], s[44:45], 0, v[134:135]
	s_mov_b32 m0, s38
	ds_read_b128 v[180:183], v178 offset:16384
	ds_read_b128 v[184:187], v178 offset:17408
	ds_read_b128 v[188:191], v178 offset:18432
	ds_read_b128 v[192:195], v178 offset:19456
	ds_read_b128 v[202:205], v178 offset:20480
	ds_read_b128 v[206:209], v178 offset:21504
	ds_read_b128 v[210:213], v178 offset:22528
	ds_read_b128 v[214:217], v178 offset:23552
	global_load_lds_dwordx4 v[218:219], off
	s_add_i32 m0, s38, 0x2000
	s_add_u32 s38, s44, 0x40000
	v_lshl_add_u64 v[220:221], s[44:45], 0, v[130:131]
	s_addc_u32 s39, s45, 0
	s_add_i32 s18, s18, s91
	global_load_lds_dwordx4 v[220:221], off
	v_lshl_add_u64 v[222:223], s[38:39], 0, v[134:135]
	s_mov_b32 m0, s18
	v_lshl_add_u64 v[224:225], s[80:81], 0, v[132:133]
	global_load_lds_dwordx4 v[222:223], off
	v_lshl_add_u64 v[222:223], s[38:39], 0, v[130:131]
	s_add_i32 m0, s18, 0x2000
	s_nop 0
	global_load_lds_dwordx4 v[222:223], off
	v_lshl_add_u64 v[222:223], s[80:81], 0, v[136:137]
	s_mov_b32 m0, s92
	s_nop 0
	global_load_lds_dwordx4 v[222:223], off
	s_mov_b32 m0, s93
	s_nop 0
	global_load_lds_dwordx4 v[224:225], off
	s_waitcnt vmcnt(8)
	s_waitcnt lgkmcnt(0)
	s_barrier
; #define PG8_STAGE(bufoff, gbase, voff) do { _Pragma("unroll") for (int _i = 0; _i < 2; ++_i) \
;         __builtin_amdgcn_global_load_lds((const unsigned*)((const char*)(gbase) + (voff)[_i]), (PG8_LAS unsigned*)(lds + (bufoff) + ldsw + _i * 8192), 16, 0, 0); } while (0)
; #define PG8_LDA(dst, b, h) do { _Pragma("unroll") for (int m = 0; m < 4; ++m) _Pragma("unroll") for (int k = 0; k < 2; ++k) dst[m][k] = *(const PG8_LAS bf16x8*)(lds + PG8_SA(b, h) + aoff + m * 2048 + k * 1024); } while (0)
; #define PG8_LDB(dst, b, h) do { _Pragma("unroll") for (int n = 0; n < 2; ++n) _Pragma("unroll") for (int k = 0; k < 2; ++k) dst[n][k] = *(const PG8_LAS bf16x8*)(lds + PG8_SB(b, h) + boff + n * 2048 + k * 1024); } while (0)
; #define PG8_MMA(ai, bj, At, Bt) do { __builtin_amdgcn_s_setprio(1); _Pragma("unroll") for (int m = 0; m < 4; ++m) _Pragma("unroll") for (int n = 0; n < 2; ++n) _Pragma("unroll") for (int k = 0; k < 2; ++k) \
;         acc[ai][bj][m][n] = __builtin_amdgcn_mfma_f32_16x16x32_bf16(Bt[n][k], At[m][k], acc[ai][bj][m][n], 0, 0, 0); __builtin_amdgcn_s_setprio(0); } while (0)
; #define PG8_WAIT_V(n) asm volatile("s_waitcnt vmcnt(" #n ")" ::: "memory")
; #define PG8_WAIT_L(n) asm volatile("s_waitcnt lgkmcnt(" #n ")" ::: "memory")
; #define PG8_BAR __builtin_amdgcn_s_barrier()
; #define PG8_SCHED __builtin_amdgcn_sched_barrier(0)
; template <class Epi, class Sched, bool ALIGN_EPI = false, bool SP2 = false>
; __device__ __forceinline__ void gemm_phase(PG8_LAS unsigned char* lds, const Gemm g, const Sched& S, const Epi& E) {
;     ...
;             PG8_WAIT_V(8); PG8_WAIT_L(0); PG8_BAR; PG8_MMA(1, 0, At, B0); PG8_MMA(1, 1, At, B1); PG8_BAR; PG8_SCHED;
;             PG8_LDB(B0, 1, 0); PG8_LDB(B1, 1, 1); PG8_SCHED; PG8_LDA(At, 1, 0); PG8_STAGE(PG8_SA(0, 1), a2 + hstep, voffA);
;             PG8_WAIT_V(8); PG8_WAIT_L(0); PG8_BAR; PG8_MMA(0, 0, At, B0); PG8_MMA(0, 1, At, B1); PG8_BAR; PG8_SCHED;
	s_setprio 1
	v_mfma_f32_16x16x32_bf16 v[62:65], v[160:163], v[180:183], v[62:65]
	v_mfma_f32_16x16x32_bf16 v[62:65], v[164:167], v[184:187], v[62:65]
	v_mfma_f32_16x16x32_bf16 v[46:49], v[160:163], v[188:191], v[46:49]
	v_mfma_f32_16x16x32_bf16 v[46:49], v[164:167], v[192:195], v[46:49]
	v_mfma_f32_16x16x32_bf16 v[30:33], v[160:163], v[202:205], v[30:33]
	v_mfma_f32_16x16x32_bf16 v[30:33], v[164:167], v[206:209], v[30:33]
	v_mfma_f32_16x16x32_bf16 v[10:13], v[160:163], v[210:213], v[10:13]
	v_mfma_f32_16x16x32_bf16 v[10:13], v[164:167], v[214:217], v[10:13]
	v_mfma_f32_16x16x32_bf16 v[58:61], v[168:171], v[180:183], v[58:61]
	v_mfma_f32_16x16x32_bf16 v[58:61], v[172:175], v[184:187], v[58:61]
	v_mfma_f32_16x16x32_bf16 v[42:45], v[168:171], v[188:191], v[42:45]
	v_mfma_f32_16x16x32_bf16 v[42:45], v[172:175], v[192:195], v[42:45]
	v_mfma_f32_16x16x32_bf16 v[26:29], v[168:171], v[202:205], v[26:29]
	v_mfma_f32_16x16x32_bf16 v[26:29], v[172:175], v[206:209], v[26:29]
	v_mfma_f32_16x16x32_bf16 v[14:17], v[168:171], v[210:213], v[14:17]
	v_mfma_f32_16x16x32_bf16 v[14:17], v[172:175], v[214:217], v[14:17]
	v_mfma_f32_16x16x32_bf16 v[54:57], v[144:147], v[180:183], v[54:57]
	v_mfma_f32_16x16x32_bf16 v[54:57], v[148:151], v[184:187], v[54:57]
	v_mfma_f32_16x16x32_bf16 v[38:41], v[144:147], v[188:191], v[38:41]
	v_mfma_f32_16x16x32_bf16 v[38:41], v[148:151], v[192:195], v[38:41]
	v_mfma_f32_16x16x32_bf16 v[22:25], v[144:147], v[202:205], v[22:25]
	v_mfma_f32_16x16x32_bf16 v[22:25], v[148:151], v[206:209], v[22:25]
	v_mfma_f32_16x16x32_bf16 v[6:9], v[144:147], v[210:213], v[6:9]
	v_mfma_f32_16x16x32_bf16 v[6:9], v[148:151], v[214:217], v[6:9]
	v_mfma_f32_16x16x32_bf16 v[50:53], v[152:155], v[180:183], v[50:53]
	v_mfma_f32_16x16x32_bf16 v[50:53], v[156:159], v[184:187], v[50:53]
	v_mfma_f32_16x16x32_bf16 v[34:37], v[152:155], v[188:191], v[34:37]
	v_mfma_f32_16x16x32_bf16 v[34:37], v[156:159], v[192:195], v[34:37]
	v_mfma_f32_16x16x32_bf16 v[18:21], v[152:155], v[202:205], v[18:21]
	v_mfma_f32_16x16x32_bf16 v[18:21], v[156:159], v[206:209], v[18:21]
	v_mfma_f32_16x16x32_bf16 v[2:5], v[152:155], v[210:213], v[2:5]
	v_mfma_f32_16x16x32_bf16 v[2:5], v[156:159], v[214:217], v[2:5]
	s_setprio 0
	s_barrier
	s_add_i32 s18, 0, 0x18000
	v_add_u32_e32 v0, s18, v176
	s_add_i32 vcc_lo, 0, 0x1c000
	ds_read_b128 v[144:147], v0
	ds_read_b128 v[148:151], v0 offset:1024
	ds_read_b128 v[152:155], v0 offset:2048
	ds_read_b128 v[156:159], v0 offset:3072
	v_add_u32_e32 v0, vcc_lo, v176
	ds_read_b128 v[160:163], v0
	ds_read_b128 v[164:167], v0 offset:1024
	ds_read_b128 v[168:171], v0 offset:2048
	ds_read_b128 v[172:175], v0 offset:3072
	s_add_u32 s38, s80, 0x40000
	s_addc_u32 s39, s81, 0
	s_mov_b32 m0, s94
	v_lshl_add_u64 v[226:227], s[38:39], 0, v[136:137]
	ds_read_b128 v[180:183], v178 offset:32768
	ds_read_b128 v[184:187], v178 offset:33792
	ds_read_b128 v[188:191], v178 offset:34816
	ds_read_b128 v[192:195], v178 offset:35840
	ds_read_b128 v[202:205], v178 offset:36864
	ds_read_b128 v[206:209], v178 offset:37888
	ds_read_b128 v[210:213], v178 offset:38912
	ds_read_b128 v[214:217], v178 offset:39936
	global_load_lds_dwordx4 v[226:227], off
	v_lshl_add_u64 v[226:227], s[38:39], 0, v[132:133]
	s_mov_b32 m0, s95
	s_nop 0
	global_load_lds_dwordx4 v[226:227], off
	s_waitcnt vmcnt(8)
	s_waitcnt lgkmcnt(0)
	s_barrier
	s_setprio 1
	v_mfma_f32_16x16x32_bf16 v[126:129], v[160:163], v[180:183], v[126:129]
	v_mfma_f32_16x16x32_bf16 v[126:129], v[164:167], v[184:187], v[126:129]
	v_mfma_f32_16x16x32_bf16 v[110:113], v[160:163], v[188:191], v[110:113]
	v_mfma_f32_16x16x32_bf16 v[110:113], v[164:167], v[192:195], v[110:113]
	v_mfma_f32_16x16x32_bf16 v[94:97], v[160:163], v[202:205], v[94:97]
	v_mfma_f32_16x16x32_bf16 v[94:97], v[164:167], v[206:209], v[94:97]
	v_mfma_f32_16x16x32_bf16 v[78:81], v[160:163], v[210:213], v[78:81]
	v_mfma_f32_16x16x32_bf16 v[78:81], v[164:167], v[214:217], v[78:81]
	v_mfma_f32_16x16x32_bf16 v[122:125], v[168:171], v[180:183], v[122:125]
	v_mfma_f32_16x16x32_bf16 v[122:125], v[172:175], v[184:187], v[122:125]
	v_mfma_f32_16x16x32_bf16 v[106:109], v[168:171], v[188:191], v[106:109]
	v_mfma_f32_16x16x32_bf16 v[106:109], v[172:175], v[192:195], v[106:109]
	v_mfma_f32_16x16x32_bf16 v[90:93], v[168:171], v[202:205], v[90:93]
	v_mfma_f32_16x16x32_bf16 v[90:93], v[172:175], v[206:209], v[90:93]
	v_mfma_f32_16x16x32_bf16 v[74:77], v[168:171], v[210:213], v[74:77]
	v_mfma_f32_16x16x32_bf16 v[74:77], v[172:175], v[214:217], v[74:77]
	v_mfma_f32_16x16x32_bf16 v[118:121], v[144:147], v[180:183], v[118:121]
	v_mfma_f32_16x16x32_bf16 v[118:121], v[148:151], v[184:187], v[118:121]
	v_mfma_f32_16x16x32_bf16 v[102:105], v[144:147], v[188:191], v[102:105]
	v_mfma_f32_16x16x32_bf16 v[102:105], v[148:151], v[192:195], v[102:105]
	v_mfma_f32_16x16x32_bf16 v[86:89], v[144:147], v[202:205], v[86:89]
	v_mfma_f32_16x16x32_bf16 v[86:89], v[148:151], v[206:209], v[86:89]
	v_mfma_f32_16x16x32_bf16 v[70:73], v[144:147], v[210:213], v[70:73]
	v_mfma_f32_16x16x32_bf16 v[70:73], v[148:151], v[214:217], v[70:73]
	v_mfma_f32_16x16x32_bf16 v[114:117], v[152:155], v[180:183], v[114:117]
	v_mfma_f32_16x16x32_bf16 v[114:117], v[156:159], v[184:187], v[114:117]
	v_mfma_f32_16x16x32_bf16 v[98:101], v[152:155], v[188:191], v[98:101]
	v_mfma_f32_16x16x32_bf16 v[98:101], v[156:159], v[192:195], v[98:101]
	v_mfma_f32_16x16x32_bf16 v[82:85], v[152:155], v[202:205], v[82:85]
	v_mfma_f32_16x16x32_bf16 v[82:85], v[156:159], v[206:209], v[82:85]
	v_mfma_f32_16x16x32_bf16 v[66:69], v[152:155], v[210:213], v[66:69]
	v_mfma_f32_16x16x32_bf16 v[66:69], v[156:159], v[214:217], v[66:69]
	s_setprio 0
	s_barrier
; #define PG8_STAGE(bufoff, gbase, voff) do { _Pragma("unroll") for (int _i = 0; _i < 2; ++_i) \
;         __builtin_amdgcn_global_load_lds((const unsigned*)((const char*)(gbase) + (voff)[_i]), (PG8_LAS unsigned*)(lds + (bufoff) + ldsw + _i * 8192), 16, 0, 0); } while (0)
; #define PG8_LDA(dst, b, h) do { _Pragma("unroll") for (int m = 0; m < 4; ++m) _Pragma("unroll") for (int k = 0; k < 2; ++k) dst[m][k] = *(const PG8_LAS bf16x8*)(lds + PG8_SA(b, h) + aoff + m * 2048 + k * 1024); } while (0)
; #define PG8_MMA(ai, bj, At, Bt) do { __builtin_amdgcn_s_setprio(1); _Pragma("unroll") for (int m = 0; m < 4; ++m) _Pragma("unroll") for (int n = 0; n < 2; ++n) _Pragma("unroll") for (int k = 0; k < 2; ++k) \
;         acc[ai][bj][m][n] = __builtin_amdgcn_mfma_f32_16x16x32_bf16(Bt[n][k], At[m][k], acc[ai][bj][m][n], 0, 0, 0); __builtin_amdgcn_s_setprio(0); } while (0)
; #define PG8_WAIT_V(n) asm volatile("s_waitcnt vmcnt(" #n ")" ::: "memory")
; #define PG8_WAIT_L(n) asm volatile("s_waitcnt lgkmcnt(" #n ")" ::: "memory")
; #define PG8_BAR __builtin_amdgcn_s_barrier()
; #define PG8_SCHED __builtin_amdgcn_sched_barrier(0)
; template <class Epi, class Sched, bool ALIGN_EPI = false, bool SP2 = false>
; __device__ __forceinline__ void gemm_phase(PG8_LAS unsigned char* lds, const Gemm g, const Sched& S, const Epi& E) {
;     ...
;             PG8_LDA(At, 1, 1); PG8_STAGE(PG8_SB(1, 0), b3, voffB); PG8_STAGE(PG8_SB(1, 1), b3 + hstep, voffB); PG8_STAGE(PG8_SA(1, 0), a3, voffA);
;             PG8_WAIT_V(8); PG8_WAIT_L(0); PG8_BAR; PG8_MMA(1, 0, At, B0); PG8_MMA(1, 1, At, B1); PG8_BAR; PG8_SCHED;
;     ...
;         if constexpr (ALIGN_EPI) { if (wr == 0) PG8_BAR; }
	s_add_i32 s18, s18, s91
	v_lshl_add_u64 v[218:219], v[218:219], 0, s[30:31]
	s_mov_b32 m0, s18
	ds_read_b128 v[180:183], v178 offset:49152
	ds_read_b128 v[184:187], v178 offset:50176
	ds_read_b128 v[188:191], v178 offset:51200
	ds_read_b128 v[192:195], v178 offset:52224
	ds_read_b128 v[202:205], v178 offset:53248
	ds_read_b128 v[206:209], v178 offset:54272
	ds_read_b128 v[210:213], v178 offset:55296
	ds_read_b128 v[214:217], v178 offset:56320
	global_load_lds_dwordx4 v[218:219], off
	s_add_i32 m0, s18, 0x2000
	s_add_u32 s38, s44, 0x40080
	v_lshl_add_u64 v[218:219], v[220:221], 0, s[30:31]
	s_addc_u32 s39, s45, 0
	s_add_i32 s18, vcc_lo, s91
	global_load_lds_dwordx4 v[218:219], off
	v_lshl_add_u64 v[218:219], s[38:39], 0, v[134:135]
	s_mov_b32 m0, s18
	s_nop 0
	global_load_lds_dwordx4 v[218:219], off
	v_lshl_add_u64 v[218:219], s[38:39], 0, v[130:131]
	s_add_i32 m0, s18, 0x2000
	s_nop 0
	global_load_lds_dwordx4 v[218:219], off
	v_lshl_add_u64 v[218:219], v[222:223], 0, s[30:31]
	s_mov_b32 m0, s7
	s_nop 0
	global_load_lds_dwordx4 v[218:219], off
	v_lshl_add_u64 v[218:219], v[224:225], 0, s[30:31]
	s_mov_b32 m0, s96
	s_nop 0
	global_load_lds_dwordx4 v[218:219], off
	s_waitcnt vmcnt(8)
	s_waitcnt lgkmcnt(0)
	s_barrier
	s_setprio 1
	v_mfma_f32_16x16x32_bf16 v[62:65], v[160:163], v[180:183], v[62:65]
	v_mfma_f32_16x16x32_bf16 v[62:65], v[164:167], v[184:187], v[62:65]
	v_mfma_f32_16x16x32_bf16 v[46:49], v[160:163], v[188:191], v[46:49]
	v_mfma_f32_16x16x32_bf16 v[46:49], v[164:167], v[192:195], v[46:49]
	v_mfma_f32_16x16x32_bf16 v[30:33], v[160:163], v[202:205], v[30:33]
	v_mfma_f32_16x16x32_bf16 v[30:33], v[164:167], v[206:209], v[30:33]
	v_mfma_f32_16x16x32_bf16 v[10:13], v[160:163], v[210:213], v[10:13]
	v_mfma_f32_16x16x32_bf16 v[10:13], v[164:167], v[214:217], v[10:13]
	v_mfma_f32_16x16x32_bf16 v[58:61], v[168:171], v[180:183], v[58:61]
	v_mfma_f32_16x16x32_bf16 v[58:61], v[172:175], v[184:187], v[58:61]
	v_mfma_f32_16x16x32_bf16 v[42:45], v[168:171], v[188:191], v[42:45]
	v_mfma_f32_16x16x32_bf16 v[42:45], v[172:175], v[192:195], v[42:45]
	v_mfma_f32_16x16x32_bf16 v[26:29], v[168:171], v[202:205], v[26:29]
	v_mfma_f32_16x16x32_bf16 v[26:29], v[172:175], v[206:209], v[26:29]
	v_mfma_f32_16x16x32_bf16 v[14:17], v[168:171], v[210:213], v[14:17]
	v_mfma_f32_16x16x32_bf16 v[14:17], v[172:175], v[214:217], v[14:17]
	v_mfma_f32_16x16x32_bf16 v[54:57], v[144:147], v[180:183], v[54:57]
	v_mfma_f32_16x16x32_bf16 v[54:57], v[148:151], v[184:187], v[54:57]
	v_mfma_f32_16x16x32_bf16 v[38:41], v[144:147], v[188:191], v[38:41]
	v_mfma_f32_16x16x32_bf16 v[38:41], v[148:151], v[192:195], v[38:41]
	v_mfma_f32_16x16x32_bf16 v[22:25], v[144:147], v[202:205], v[22:25]
	v_mfma_f32_16x16x32_bf16 v[22:25], v[148:151], v[206:209], v[22:25]
	v_mfma_f32_16x16x32_bf16 v[6:9], v[144:147], v[210:213], v[6:9]
	v_mfma_f32_16x16x32_bf16 v[6:9], v[148:151], v[214:217], v[6:9]
	v_mfma_f32_16x16x32_bf16 v[50:53], v[152:155], v[180:183], v[50:53]
	v_mfma_f32_16x16x32_bf16 v[50:53], v[156:159], v[184:187], v[50:53]
	v_mfma_f32_16x16x32_bf16 v[34:37], v[152:155], v[188:191], v[34:37]
	v_mfma_f32_16x16x32_bf16 v[34:37], v[156:159], v[192:195], v[34:37]
	v_mfma_f32_16x16x32_bf16 v[18:21], v[152:155], v[202:205], v[18:21]
	v_mfma_f32_16x16x32_bf16 v[18:21], v[156:159], v[206:209], v[18:21]
	v_mfma_f32_16x16x32_bf16 v[2:5], v[152:155], v[210:213], v[2:5]
	v_mfma_f32_16x16x32_bf16 v[2:5], v[156:159], v[214:217], v[2:5]
	s_setprio 0
	s_barrier
	s_add_i32 s85, s85, 2
	s_add_u32 s46, s46, 0x100
	s_addc_u32 s47, s47, 0
	s_add_u32 s83, s83, 0x100
	s_addc_u32 s84, s84, 0
	s_cmp_gt_u32 s85, 13
	s_cbranch_scc0 .LBB0_132
	s_and_b64 vcc, exec, s[10:11]
	s_cbranch_vccz .LBB0_135
	s_barrier

; #define PG8_STAGE(bufoff, gbase, voff) do { _Pragma("unroll") for (int _i = 0; _i < 2; ++_i) \
;         __builtin_amdgcn_global_load_lds((const unsigned*)((const char*)(gbase) + (voff)[_i]), (PG8_LAS unsigned*)(lds + (bufoff) + ldsw + _i * 8192), 16, 0, 0); } while (0)
; #define PG8_LDA(dst, b, h) do { _Pragma("unroll") for (int m = 0; m < 4; ++m) _Pragma("unroll") for (int k = 0; k < 2; ++k) dst[m][k] = *(const PG8_LAS bf16x8*)(lds + PG8_SA(b, h) + aoff + m * 2048 + k * 1024); } while (0)
; #define PG8_LDB(dst, b, h) do { _Pragma("unroll") for (int n = 0; n < 2; ++n) _Pragma("unroll") for (int k = 0; k < 2; ++k) dst[n][k] = *(const PG8_LAS bf16x8*)(lds + PG8_SB(b, h) + boff + n * 2048 + k * 1024); } while (0)
; #define PG8_MMA(ai, bj, At, Bt) do { __builtin_amdgcn_s_setprio(1); _Pragma("unroll") for (int m = 0; m < 4; ++m) _Pragma("unroll") for (int n = 0; n < 2; ++n) _Pragma("unroll") for (int k = 0; k < 2; ++k) \
;         acc[ai][bj][m][n] = __builtin_amdgcn_mfma_f32_16x16x32_bf16(Bt[n][k], At[m][k], acc[ai][bj][m][n], 0, 0, 0); __builtin_amdgcn_s_setprio(0); } while (0)
; #define PG8_WAIT_V(n) asm volatile("s_waitcnt vmcnt(" #n ")" ::: "memory")
; #define PG8_WAIT_L(n) asm volatile("s_waitcnt lgkmcnt(" #n ")" ::: "memory")
; template <class Epi, class Sched, bool ALIGN_EPI = false, bool SP2 = false>
; __device__ __forceinline__ void gemm_phase(PG8_LAS unsigned char* lds, const Gemm g, const Sched& S, const Epi& E) {
;     ...
;             const bool last = (t == nt - 2);
;             const char* a1 = cA + (size_t)(t + 1) * kstep;
;             const char* a2 = last ? nA : cA + (size_t)(t + 2) * kstep; const char* b2 = last ? nB : cB + (size_t)(t + 2) * kstep;
;             const char* a3 = a2 + kstep; const char* b3 = b2 + kstep;
;             if (last && has_next) S.a_ready(nxt);
;             if constexpr (SP2) {
;             PG8_LDB(B0, 0, 0); PG8_LDB(B1, 0, 1); PG8_SCHED; PG8_LDA(At, 0, 0); PG8_STAGE(PG8_SA(1, 1), a1 + hstep, voffA);
;             PG8_WAIT_V(8); PG8_WAIT_L(0); PG8_BAR; PG8_MMA(0, 0, At, B0); PG8_MMA(0, 1, At, B1); PG8_BAR; PG8_SCHED;
;             PG8_LDA(At, 0, 1); PG8_STAGE(PG8_SB(0, 0), b2, voffB); PG8_STAGE(PG8_SB(0, 1), b2 + hstep, voffB); PG8_STAGE(PG8_SA(0, 0), a2, voffA);
;             PG8_WAIT_V(8); PG8_WAIT_L(0); PG8_BAR; PG8_MMA(1, 0, At, B0); PG8_MMA(1, 1, At, B1); PG8_BAR; PG8_SCHED;
.LBB0_220:
	s_add_u32 s18, s60, 0xfffc0080
	s_addc_u32 s38, s61, -1
	s_add_i32 s39, 0, 0x10000
	s_cmp_eq_u32 s82, 12
	s_cselect_b32 s65, s47, s38
	s_cselect_b32 s64, s78, s18
	v_add_u32_e32 v145, s39, v141
	s_cselect_b32 s57, s49, s81
	s_cselect_b32 s56, s79, s80
	s_add_i32 s18, 0, 0x14000
	ds_read_b128 v[146:149], v145
	ds_read_b128 v[150:153], v145 offset:1024
	ds_read_b128 v[154:157], v145 offset:2048
	ds_read_b128 v[158:161], v145 offset:3072
	v_add_u32_e32 v145, s18, v141
	ds_read_b128 v[162:165], v145
	ds_read_b128 v[166:169], v145 offset:1024
	ds_read_b128 v[170:173], v145 offset:2048
	ds_read_b128 v[174:177], v145 offset:3072
	v_lshl_add_u64 v[194:195], s[60:61], 0, v[136:137]
	s_add_i32 m0, s29, 0xc000
	ds_read_b128 v[178:181], v144
	ds_read_b128 v[182:185], v144 offset:1024
	ds_read_b128 v[186:189], v144 offset:2048
	ds_read_b128 v[190:193], v144 offset:3072
	ds_read_b128 v[202:205], v144 offset:4096
	ds_read_b128 v[206:209], v144 offset:5120
	ds_read_b128 v[210:213], v144 offset:6144
	ds_read_b128 v[214:217], v144 offset:7168
	global_load_lds_dwordx4 v[194:195], off
	v_lshl_add_u64 v[194:195], s[60:61], 0, v[138:139]
	s_add_i32 m0, s29, 0xe000
	s_nop 0
	global_load_lds_dwordx4 v[194:195], off
	s_waitcnt vmcnt(8)
	s_waitcnt lgkmcnt(0)
	s_barrier
	s_setprio 1
	v_mfma_f32_16x16x32_bf16 v[122:125], v[162:165], v[178:181], v[122:125]
	v_mfma_f32_16x16x32_bf16 v[122:125], v[166:169], v[182:185], v[122:125]
	v_mfma_f32_16x16x32_bf16 v[106:109], v[162:165], v[186:189], v[106:109]
	v_mfma_f32_16x16x32_bf16 v[106:109], v[166:169], v[190:193], v[106:109]
	v_mfma_f32_16x16x32_bf16 v[90:93], v[162:165], v[202:205], v[90:93]
	v_mfma_f32_16x16x32_bf16 v[90:93], v[166:169], v[206:209], v[90:93]
	v_mfma_f32_16x16x32_bf16 v[74:77], v[162:165], v[210:213], v[74:77]
	v_mfma_f32_16x16x32_bf16 v[74:77], v[166:169], v[214:217], v[74:77]
	v_mfma_f32_16x16x32_bf16 v[126:129], v[170:173], v[178:181], v[126:129]
	v_mfma_f32_16x16x32_bf16 v[126:129], v[174:177], v[182:185], v[126:129]
	v_mfma_f32_16x16x32_bf16 v[110:113], v[170:173], v[186:189], v[110:113]
	v_mfma_f32_16x16x32_bf16 v[110:113], v[174:177], v[190:193], v[110:113]
	v_mfma_f32_16x16x32_bf16 v[94:97], v[170:173], v[202:205], v[94:97]
	v_mfma_f32_16x16x32_bf16 v[94:97], v[174:177], v[206:209], v[94:97]
	v_mfma_f32_16x16x32_bf16 v[78:81], v[170:173], v[210:213], v[78:81]
	v_mfma_f32_16x16x32_bf16 v[78:81], v[174:177], v[214:217], v[78:81]
	v_mfma_f32_16x16x32_bf16 v[114:117], v[146:149], v[178:181], v[114:117]
	v_mfma_f32_16x16x32_bf16 v[114:117], v[150:153], v[182:185], v[114:117]
	v_mfma_f32_16x16x32_bf16 v[98:101], v[146:149], v[186:189], v[98:101]
	v_mfma_f32_16x16x32_bf16 v[98:101], v[150:153], v[190:193], v[98:101]
	v_mfma_f32_16x16x32_bf16 v[82:85], v[146:149], v[202:205], v[82:85]
	v_mfma_f32_16x16x32_bf16 v[82:85], v[150:153], v[206:209], v[82:85]
	v_mfma_f32_16x16x32_bf16 v[66:69], v[146:149], v[210:213], v[66:69]
	v_mfma_f32_16x16x32_bf16 v[66:69], v[150:153], v[214:217], v[66:69]
	v_mfma_f32_16x16x32_bf16 v[118:121], v[154:157], v[178:181], v[118:121]
	v_mfma_f32_16x16x32_bf16 v[118:121], v[158:161], v[182:185], v[118:121]
	v_mfma_f32_16x16x32_bf16 v[102:105], v[154:157], v[186:189], v[102:105]
	v_mfma_f32_16x16x32_bf16 v[102:105], v[158:161], v[190:193], v[102:105]
	v_mfma_f32_16x16x32_bf16 v[86:89], v[154:157], v[202:205], v[86:89]
	v_mfma_f32_16x16x32_bf16 v[86:89], v[158:161], v[206:209], v[86:89]
	v_mfma_f32_16x16x32_bf16 v[70:73], v[154:157], v[210:213], v[70:73]
	v_mfma_f32_16x16x32_bf16 v[70:73], v[158:161], v[214:217], v[70:73]
	s_setprio 0
	s_barrier
	s_add_i32 s38, s39, s27
	v_lshl_add_u64 v[194:195], s[56:57], 0, v[0:1]
	s_mov_b32 m0, s38
	ds_read_b128 v[178:181], v144 offset:16384
	ds_read_b128 v[182:185], v144 offset:17408
	ds_read_b128 v[186:189], v144 offset:18432
	ds_read_b128 v[190:193], v144 offset:19456
	ds_read_b128 v[202:205], v144 offset:20480
	ds_read_b128 v[206:209], v144 offset:21504
	ds_read_b128 v[210:213], v144 offset:22528
	ds_read_b128 v[214:217], v144 offset:23552
	global_load_lds_dwordx4 v[194:195], off
	s_add_i32 m0, s38, 0x2000
	s_add_u32 s38, s56, 0x40000
	v_lshl_add_u64 v[218:219], s[56:57], 0, v[130:131]
	s_addc_u32 s39, s57, 0
	s_add_i32 s18, s18, s27
	global_load_lds_dwordx4 v[218:219], off
	v_lshl_add_u64 v[220:221], s[38:39], 0, v[0:1]
	s_mov_b32 m0, s18
	v_lshl_add_u64 v[222:223], s[64:65], 0, v[132:133]
	global_load_lds_dwordx4 v[220:221], off
	v_lshl_add_u64 v[220:221], s[38:39], 0, v[130:131]
	s_add_i32 m0, s18, 0x2000
	s_nop 0
	global_load_lds_dwordx4 v[220:221], off
	v_lshl_add_u64 v[220:221], s[64:65], 0, v[134:135]
	s_mov_b32 m0, s29
	s_nop 0
	global_load_lds_dwordx4 v[220:221], off
	s_mov_b32 m0, s33
	s_nop 0
	global_load_lds_dwordx4 v[222:223], off
	s_waitcnt vmcnt(8)
	s_waitcnt lgkmcnt(0)
	s_barrier
; #define PG8_STAGE(bufoff, gbase, voff) do { _Pragma("unroll") for (int _i = 0; _i < 2; ++_i) \
;         __builtin_amdgcn_global_load_lds((const unsigned*)((const char*)(gbase) + (voff)[_i]), (PG8_LAS unsigned*)(lds + (bufoff) + ldsw + _i * 8192), 16, 0, 0); } while (0)
; #define PG8_LDA(dst, b, h) do { _Pragma("unroll") for (int m = 0; m < 4; ++m) _Pragma("unroll") for (int k = 0; k < 2; ++k) dst[m][k] = *(const PG8_LAS bf16x8*)(lds + PG8_SA(b, h) + aoff + m * 2048 + k * 1024); } while (0)
; #define PG8_LDB(dst, b, h) do { _Pragma("unroll") for (int n = 0; n < 2; ++n) _Pragma("unroll") for (int k = 0; k < 2; ++k) dst[n][k] = *(const PG8_LAS bf16x8*)(lds + PG8_SB(b, h) + boff + n * 2048 + k * 1024); } while (0)
; #define PG8_MMA(ai, bj, At, Bt) do { __builtin_amdgcn_s_setprio(1); _Pragma("unroll") for (int m = 0; m < 4; ++m) _Pragma("unroll") for (int n = 0; n < 2; ++n) _Pragma("unroll") for (int k = 0; k < 2; ++k) \
;         acc[ai][bj][m][n] = __builtin_amdgcn_mfma_f32_16x16x32_bf16(Bt[n][k], At[m][k], acc[ai][bj][m][n], 0, 0, 0); __builtin_amdgcn_s_setprio(0); } while (0)
; #define PG8_WAIT_V(n) asm volatile("s_waitcnt vmcnt(" #n ")" ::: "memory")
; #define PG8_WAIT_L(n) asm volatile("s_waitcnt lgkmcnt(" #n ")" ::: "memory")
; #define PG8_BAR __builtin_amdgcn_s_barrier()
; #define PG8_SCHED __builtin_amdgcn_sched_barrier(0)
; template <class Epi, class Sched, bool ALIGN_EPI = false, bool SP2 = false>
; __device__ __forceinline__ void gemm_phase(PG8_LAS unsigned char* lds, const Gemm g, const Sched& S, const Epi& E) {
;     ...
;             PG8_WAIT_V(8); PG8_WAIT_L(0); PG8_BAR; PG8_MMA(1, 0, At, B0); PG8_MMA(1, 1, At, B1); PG8_BAR; PG8_SCHED;
;             PG8_LDB(B0, 1, 0); PG8_LDB(B1, 1, 1); PG8_SCHED; PG8_LDA(At, 1, 0); PG8_STAGE(PG8_SA(0, 1), a2 + hstep, voffA);
;             PG8_WAIT_V(8); PG8_WAIT_L(0); PG8_BAR; PG8_MMA(0, 0, At, B0); PG8_MMA(0, 1, At, B1); PG8_BAR; PG8_SCHED;
	s_setprio 1
	v_mfma_f32_16x16x32_bf16 v[58:61], v[162:165], v[178:181], v[58:61]
	v_mfma_f32_16x16x32_bf16 v[58:61], v[166:169], v[182:185], v[58:61]
	v_mfma_f32_16x16x32_bf16 v[42:45], v[162:165], v[186:189], v[42:45]
	v_mfma_f32_16x16x32_bf16 v[42:45], v[166:169], v[190:193], v[42:45]
	v_mfma_f32_16x16x32_bf16 v[26:29], v[162:165], v[202:205], v[26:29]
	v_mfma_f32_16x16x32_bf16 v[26:29], v[166:169], v[206:209], v[26:29]
	v_mfma_f32_16x16x32_bf16 v[10:13], v[162:165], v[210:213], v[10:13]
	v_mfma_f32_16x16x32_bf16 v[10:13], v[166:169], v[214:217], v[10:13]
	v_mfma_f32_16x16x32_bf16 v[62:65], v[170:173], v[178:181], v[62:65]
	v_mfma_f32_16x16x32_bf16 v[62:65], v[174:177], v[182:185], v[62:65]
	v_mfma_f32_16x16x32_bf16 v[46:49], v[170:173], v[186:189], v[46:49]
	v_mfma_f32_16x16x32_bf16 v[46:49], v[174:177], v[190:193], v[46:49]
	v_mfma_f32_16x16x32_bf16 v[30:33], v[170:173], v[202:205], v[30:33]
	v_mfma_f32_16x16x32_bf16 v[30:33], v[174:177], v[206:209], v[30:33]
	v_mfma_f32_16x16x32_bf16 v[14:17], v[170:173], v[210:213], v[14:17]
	v_mfma_f32_16x16x32_bf16 v[14:17], v[174:177], v[214:217], v[14:17]
	v_mfma_f32_16x16x32_bf16 v[50:53], v[146:149], v[178:181], v[50:53]
	v_mfma_f32_16x16x32_bf16 v[50:53], v[150:153], v[182:185], v[50:53]
	v_mfma_f32_16x16x32_bf16 v[34:37], v[146:149], v[186:189], v[34:37]
	v_mfma_f32_16x16x32_bf16 v[34:37], v[150:153], v[190:193], v[34:37]
	v_mfma_f32_16x16x32_bf16 v[18:21], v[146:149], v[202:205], v[18:21]
	v_mfma_f32_16x16x32_bf16 v[18:21], v[150:153], v[206:209], v[18:21]
	v_mfma_f32_16x16x32_bf16 v[2:5], v[146:149], v[210:213], v[2:5]
	v_mfma_f32_16x16x32_bf16 v[2:5], v[150:153], v[214:217], v[2:5]
	v_mfma_f32_16x16x32_bf16 v[54:57], v[154:157], v[178:181], v[54:57]
	v_mfma_f32_16x16x32_bf16 v[54:57], v[158:161], v[182:185], v[54:57]
	v_mfma_f32_16x16x32_bf16 v[38:41], v[154:157], v[186:189], v[38:41]
	v_mfma_f32_16x16x32_bf16 v[38:41], v[158:161], v[190:193], v[38:41]
	v_mfma_f32_16x16x32_bf16 v[22:25], v[154:157], v[202:205], v[22:25]
	v_mfma_f32_16x16x32_bf16 v[22:25], v[158:161], v[206:209], v[22:25]
	v_mfma_f32_16x16x32_bf16 v[6:9], v[154:157], v[210:213], v[6:9]
	v_mfma_f32_16x16x32_bf16 v[6:9], v[158:161], v[214:217], v[6:9]
	s_setprio 0
	s_barrier
	s_add_i32 s18, 0, 0x18000
	v_add_u32_e32 v145, s18, v141
	s_add_i32 s83, 0, 0x1c000
	ds_read_b128 v[146:149], v145
	ds_read_b128 v[150:153], v145 offset:1024
	ds_read_b128 v[154:157], v145 offset:2048
	ds_read_b128 v[158:161], v145 offset:3072
	v_add_u32_e32 v145, s83, v141
	ds_read_b128 v[162:165], v145
	ds_read_b128 v[166:169], v145 offset:1024
	ds_read_b128 v[170:173], v145 offset:2048
	ds_read_b128 v[174:177], v145 offset:3072
	s_add_u32 s38, s64, 0x40000
	s_addc_u32 s39, s65, 0
	s_mov_b32 m0, s58
	v_lshl_add_u64 v[224:225], s[38:39], 0, v[134:135]
	ds_read_b128 v[178:181], v144 offset:32768
	ds_read_b128 v[182:185], v144 offset:33792
	ds_read_b128 v[186:189], v144 offset:34816
	ds_read_b128 v[190:193], v144 offset:35840
	ds_read_b128 v[202:205], v144 offset:36864
	ds_read_b128 v[206:209], v144 offset:37888
	ds_read_b128 v[210:213], v144 offset:38912
	ds_read_b128 v[214:217], v144 offset:39936
	global_load_lds_dwordx4 v[224:225], off
	v_lshl_add_u64 v[224:225], s[38:39], 0, v[132:133]
	s_mov_b32 m0, s69
	s_nop 0
	global_load_lds_dwordx4 v[224:225], off
	s_waitcnt vmcnt(8)
	s_waitcnt lgkmcnt(0)
	s_barrier
	s_setprio 1
	v_mfma_f32_16x16x32_bf16 v[122:125], v[162:165], v[178:181], v[122:125]
	v_mfma_f32_16x16x32_bf16 v[122:125], v[166:169], v[182:185], v[122:125]
	v_mfma_f32_16x16x32_bf16 v[106:109], v[162:165], v[186:189], v[106:109]
	v_mfma_f32_16x16x32_bf16 v[106:109], v[166:169], v[190:193], v[106:109]
	v_mfma_f32_16x16x32_bf16 v[90:93], v[162:165], v[202:205], v[90:93]
	v_mfma_f32_16x16x32_bf16 v[90:93], v[166:169], v[206:209], v[90:93]
	v_mfma_f32_16x16x32_bf16 v[74:77], v[162:165], v[210:213], v[74:77]
	v_mfma_f32_16x16x32_bf16 v[74:77], v[166:169], v[214:217], v[74:77]
	v_mfma_f32_16x16x32_bf16 v[126:129], v[170:173], v[178:181], v[126:129]
	v_mfma_f32_16x16x32_bf16 v[126:129], v[174:177], v[182:185], v[126:129]
	v_mfma_f32_16x16x32_bf16 v[110:113], v[170:173], v[186:189], v[110:113]
	v_mfma_f32_16x16x32_bf16 v[110:113], v[174:177], v[190:193], v[110:113]
	v_mfma_f32_16x16x32_bf16 v[94:97], v[170:173], v[202:205], v[94:97]
	v_mfma_f32_16x16x32_bf16 v[94:97], v[174:177], v[206:209], v[94:97]
	v_mfma_f32_16x16x32_bf16 v[78:81], v[170:173], v[210:213], v[78:81]
	v_mfma_f32_16x16x32_bf16 v[78:81], v[174:177], v[214:217], v[78:81]
	v_mfma_f32_16x16x32_bf16 v[114:117], v[146:149], v[178:181], v[114:117]
	v_mfma_f32_16x16x32_bf16 v[114:117], v[150:153], v[182:185], v[114:117]
	v_mfma_f32_16x16x32_bf16 v[98:101], v[146:149], v[186:189], v[98:101]
	v_mfma_f32_16x16x32_bf16 v[98:101], v[150:153], v[190:193], v[98:101]
	v_mfma_f32_16x16x32_bf16 v[82:85], v[146:149], v[202:205], v[82:85]
	v_mfma_f32_16x16x32_bf16 v[82:85], v[150:153], v[206:209], v[82:85]
	v_mfma_f32_16x16x32_bf16 v[66:69], v[146:149], v[210:213], v[66:69]
	v_mfma_f32_16x16x32_bf16 v[66:69], v[150:153], v[214:217], v[66:69]
	v_mfma_f32_16x16x32_bf16 v[118:121], v[154:157], v[178:181], v[118:121]
	v_mfma_f32_16x16x32_bf16 v[118:121], v[158:161], v[182:185], v[118:121]
	v_mfma_f32_16x16x32_bf16 v[102:105], v[154:157], v[186:189], v[102:105]
	v_mfma_f32_16x16x32_bf16 v[102:105], v[158:161], v[190:193], v[102:105]
	v_mfma_f32_16x16x32_bf16 v[86:89], v[154:157], v[202:205], v[86:89]
	v_mfma_f32_16x16x32_bf16 v[86:89], v[158:161], v[206:209], v[86:89]
	v_mfma_f32_16x16x32_bf16 v[70:73], v[154:157], v[210:213], v[70:73]
	v_mfma_f32_16x16x32_bf16 v[70:73], v[158:161], v[214:217], v[70:73]
	s_setprio 0
	s_barrier
; #define PG8_STAGE(bufoff, gbase, voff) do { _Pragma("unroll") for (int _i = 0; _i < 2; ++_i) \
;         __builtin_amdgcn_global_load_lds((const unsigned*)((const char*)(gbase) + (voff)[_i]), (PG8_LAS unsigned*)(lds + (bufoff) + ldsw + _i * 8192), 16, 0, 0); } while (0)
; #define PG8_LDA(dst, b, h) do { _Pragma("unroll") for (int m = 0; m < 4; ++m) _Pragma("unroll") for (int k = 0; k < 2; ++k) dst[m][k] = *(const PG8_LAS bf16x8*)(lds + PG8_SA(b, h) + aoff + m * 2048 + k * 1024); } while (0)
; #define PG8_MMA(ai, bj, At, Bt) do { __builtin_amdgcn_s_setprio(1); _Pragma("unroll") for (int m = 0; m < 4; ++m) _Pragma("unroll") for (int n = 0; n < 2; ++n) _Pragma("unroll") for (int k = 0; k < 2; ++k) \
;         acc[ai][bj][m][n] = __builtin_amdgcn_mfma_f32_16x16x32_bf16(Bt[n][k], At[m][k], acc[ai][bj][m][n], 0, 0, 0); __builtin_amdgcn_s_setprio(0); } while (0)
; #define PG8_WAIT_V(n) asm volatile("s_waitcnt vmcnt(" #n ")" ::: "memory")
; #define PG8_WAIT_L(n) asm volatile("s_waitcnt lgkmcnt(" #n ")" ::: "memory")
; #define PG8_BAR __builtin_amdgcn_s_barrier()
; #define PG8_SCHED __builtin_amdgcn_sched_barrier(0)
; template <class Epi, class Sched, bool ALIGN_EPI = false, bool SP2 = false>
; __device__ __forceinline__ void gemm_phase(PG8_LAS unsigned char* lds, const Gemm g, const Sched& S, const Epi& E) {
;     ...
;             PG8_LDA(At, 1, 1); PG8_STAGE(PG8_SB(1, 0), b3, voffB); PG8_STAGE(PG8_SB(1, 1), b3 + hstep, voffB); PG8_STAGE(PG8_SA(1, 0), a3, voffA);
;             PG8_WAIT_V(8); PG8_WAIT_L(0); PG8_BAR; PG8_MMA(1, 0, At, B0); PG8_MMA(1, 1, At, B1); PG8_BAR; PG8_SCHED;
;     ...
;         if constexpr (ALIGN_EPI) { if (wr == 0) PG8_BAR; }
	s_add_i32 s18, s18, s27
	v_lshl_add_u64 v[194:195], v[194:195], 0, s[30:31]
	s_mov_b32 m0, s18
	ds_read_b128 v[178:181], v144 offset:49152
	ds_read_b128 v[182:185], v144 offset:50176
	ds_read_b128 v[186:189], v144 offset:51200
	ds_read_b128 v[190:193], v144 offset:52224
	ds_read_b128 v[202:205], v144 offset:53248
	ds_read_b128 v[206:209], v144 offset:54272
	ds_read_b128 v[210:213], v144 offset:55296
	ds_read_b128 v[214:217], v144 offset:56320
	global_load_lds_dwordx4 v[194:195], off
	s_add_i32 m0, s18, 0x2000
	s_add_u32 s38, s56, 0x40080
	v_lshl_add_u64 v[194:195], v[218:219], 0, s[30:31]
	s_addc_u32 s39, s57, 0
	s_add_i32 s18, s83, s27
	global_load_lds_dwordx4 v[194:195], off
	v_lshl_add_u64 v[194:195], s[38:39], 0, v[0:1]
	s_mov_b32 m0, s18
	s_nop 0
	global_load_lds_dwordx4 v[194:195], off
	v_lshl_add_u64 v[194:195], s[38:39], 0, v[130:131]
	s_add_i32 m0, s18, 0x2000
	s_nop 0
	global_load_lds_dwordx4 v[194:195], off
	v_lshl_add_u64 v[194:195], v[220:221], 0, s[30:31]
	s_mov_b32 m0, s71
	s_nop 0
	global_load_lds_dwordx4 v[194:195], off
	v_lshl_add_u64 v[194:195], v[222:223], 0, s[30:31]
	s_mov_b32 m0, s72
	s_nop 0
	global_load_lds_dwordx4 v[194:195], off
	s_waitcnt vmcnt(8)
	s_waitcnt lgkmcnt(0)
	s_barrier
	s_setprio 1
	v_mfma_f32_16x16x32_bf16 v[58:61], v[162:165], v[178:181], v[58:61]
	v_mfma_f32_16x16x32_bf16 v[58:61], v[166:169], v[182:185], v[58:61]
	v_mfma_f32_16x16x32_bf16 v[42:45], v[162:165], v[186:189], v[42:45]
	v_mfma_f32_16x16x32_bf16 v[42:45], v[166:169], v[190:193], v[42:45]
	v_mfma_f32_16x16x32_bf16 v[26:29], v[162:165], v[202:205], v[26:29]
	v_mfma_f32_16x16x32_bf16 v[26:29], v[166:169], v[206:209], v[26:29]
	v_mfma_f32_16x16x32_bf16 v[10:13], v[162:165], v[210:213], v[10:13]
	v_mfma_f32_16x16x32_bf16 v[10:13], v[166:169], v[214:217], v[10:13]
	v_mfma_f32_16x16x32_bf16 v[62:65], v[170:173], v[178:181], v[62:65]
	v_mfma_f32_16x16x32_bf16 v[62:65], v[174:177], v[182:185], v[62:65]
	v_mfma_f32_16x16x32_bf16 v[46:49], v[170:173], v[186:189], v[46:49]
	v_mfma_f32_16x16x32_bf16 v[46:49], v[174:177], v[190:193], v[46:49]
	v_mfma_f32_16x16x32_bf16 v[30:33], v[170:173], v[202:205], v[30:33]
	v_mfma_f32_16x16x32_bf16 v[30:33], v[174:177], v[206:209], v[30:33]
	v_mfma_f32_16x16x32_bf16 v[14:17], v[170:173], v[210:213], v[14:17]
	v_mfma_f32_16x16x32_bf16 v[14:17], v[174:177], v[214:217], v[14:17]
	v_mfma_f32_16x16x32_bf16 v[50:53], v[146:149], v[178:181], v[50:53]
	v_mfma_f32_16x16x32_bf16 v[50:53], v[150:153], v[182:185], v[50:53]
	v_mfma_f32_16x16x32_bf16 v[34:37], v[146:149], v[186:189], v[34:37]
	v_mfma_f32_16x16x32_bf16 v[34:37], v[150:153], v[190:193], v[34:37]
	v_mfma_f32_16x16x32_bf16 v[18:21], v[146:149], v[202:205], v[18:21]
	v_mfma_f32_16x16x32_bf16 v[18:21], v[150:153], v[206:209], v[18:21]
	v_mfma_f32_16x16x32_bf16 v[2:5], v[146:149], v[210:213], v[2:5]
	v_mfma_f32_16x16x32_bf16 v[2:5], v[150:153], v[214:217], v[2:5]
	v_mfma_f32_16x16x32_bf16 v[54:57], v[154:157], v[178:181], v[54:57]
	v_mfma_f32_16x16x32_bf16 v[54:57], v[158:161], v[182:185], v[54:57]
	v_mfma_f32_16x16x32_bf16 v[38:41], v[154:157], v[186:189], v[38:41]
	v_mfma_f32_16x16x32_bf16 v[38:41], v[158:161], v[190:193], v[38:41]
	v_mfma_f32_16x16x32_bf16 v[22:25], v[154:157], v[202:205], v[22:25]
	v_mfma_f32_16x16x32_bf16 v[22:25], v[158:161], v[206:209], v[22:25]
	v_mfma_f32_16x16x32_bf16 v[6:9], v[154:157], v[210:213], v[6:9]
	v_mfma_f32_16x16x32_bf16 v[6:9], v[158:161], v[214:217], v[6:9]
	s_setprio 0
	s_barrier
	s_add_i32 s82, s82, 2
	s_add_u32 s60, s60, 0x100
	s_addc_u32 s61, s61, 0
	s_add_u32 s80, s80, 0x100
	s_addc_u32 s81, s81, 0
	s_cmp_gt_u32 s82, 13
	s_cbranch_scc0 .LBB0_220
	s_and_b64 vcc, exec, s[44:45]
	s_cbranch_vccz .LBB0_223
	s_barrier

; #define PG8_STAGE(bufoff, gbase, voff) do { _Pragma("unroll") for (int _i = 0; _i < 2; ++_i) \
;         __builtin_amdgcn_global_load_lds((const unsigned*)((const char*)(gbase) + (voff)[_i]), (PG8_LAS unsigned*)(lds + (bufoff) + ldsw + _i * 8192), 16, 0, 0); } while (0)
; #define PG8_LDA(dst, b, h) do { _Pragma("unroll") for (int m = 0; m < 4; ++m) _Pragma("unroll") for (int k = 0; k < 2; ++k) dst[m][k] = *(const PG8_LAS bf16x8*)(lds + PG8_SA(b, h) + aoff + m * 2048 + k * 1024); } while (0)
; #define PG8_LDB(dst, b, h) do { _Pragma("unroll") for (int n = 0; n < 2; ++n) _Pragma("unroll") for (int k = 0; k < 2; ++k) dst[n][k] = *(const PG8_LAS bf16x8*)(lds + PG8_SB(b, h) + boff + n * 2048 + k * 1024); } while (0)
; #define PG8_MMA(ai, bj, At, Bt) do { __builtin_amdgcn_s_setprio(1); _Pragma("unroll") for (int m = 0; m < 4; ++m) _Pragma("unroll") for (int n = 0; n < 2; ++n) _Pragma("unroll") for (int k = 0; k < 2; ++k) \
;         acc[ai][bj][m][n] = __builtin_amdgcn_mfma_f32_16x16x32_bf16(Bt[n][k], At[m][k], acc[ai][bj][m][n], 0, 0, 0); __builtin_amdgcn_s_setprio(0); } while (0)
; #define PG8_WAIT_V(n) asm volatile("s_waitcnt vmcnt(" #n ")" ::: "memory")
; #define PG8_WAIT_L(n) asm volatile("s_waitcnt lgkmcnt(" #n ")" ::: "memory")
; #define PG8_BAR __builtin_amdgcn_s_barrier()
; template <class Epi, class Sched, bool ALIGN_EPI = false, bool SP2 = false>
; __device__ __forceinline__ void gemm_phase(PG8_LAS unsigned char* lds, const Gemm g, const Sched& S, const Epi& E) {
;     ...
;             const char* a1 = cA + (size_t)(t + 1) * kstep;
;             const char* a2 = last ? nA : cA + (size_t)(t + 2) * kstep; const char* b2 = last ? nB : cB + (size_t)(t + 2) * kstep;
;             const char* a3 = a2 + kstep; const char* b3 = b2 + kstep;
;             if (last && has_next) S.a_ready(nxt);
;             if constexpr (SP2) {
;             PG8_LDB(B0, 0, 0); PG8_LDB(B1, 0, 1); PG8_SCHED; PG8_LDA(At, 0, 0); PG8_STAGE(PG8_SA(1, 1), a1 + hstep, voffA);
;             PG8_WAIT_V(8); PG8_WAIT_L(0); PG8_BAR; PG8_MMA(0, 0, At, B0); PG8_MMA(0, 1, At, B1); PG8_BAR; PG8_SCHED;
;             PG8_LDA(At, 0, 1); PG8_STAGE(PG8_SB(0, 0), b2, voffB); PG8_STAGE(PG8_SB(0, 1), b2 + hstep, voffB); PG8_STAGE(PG8_SA(0, 0), a2, voffA);
;             PG8_WAIT_V(8); PG8_WAIT_L(0); PG8_BAR; PG8_MMA(1, 0, At, B0); PG8_MMA(1, 1, At, B1); PG8_BAR; PG8_SCHED;
.LBB0_274:
	s_add_i32 vcc_lo, s46, 2
	s_add_u32 s38, s48, 0x80
	s_addc_u32 s39, s49, 0
	s_add_i32 vcc_hi, 0, 0x10000
	s_cmp_eq_u32 s99, s46
	s_cselect_b32 s47, s81, s39
	s_cselect_b32 s46, s80, s38
	s_cselect_b32 s39, s83, s51
	s_cselect_b32 s38, s82, s50
	s_add_i32 s18, 0, 0x14000
	v_add_u32_e32 v142, vcc_hi, v245
	v_add_u32_e32 v158, s18, v245
	ds_read_b128 v[110:113], v142
	ds_read_b128 v[118:121], v142 offset:1024
	ds_read_b128 v[138:141], v142 offset:2048
	ds_read_b128 v[142:145], v142 offset:3072
	ds_read_b128 v[146:149], v158
	ds_read_b128 v[150:153], v158 offset:1024
	ds_read_b128 v[154:157], v158 offset:2048
	ds_read_b128 v[158:161], v158 offset:3072
	v_lshl_add_u64 v[210:211], s[48:49], 0, v[206:207]
	s_add_i32 m0, s92, 0xc000
	ds_read_b128 v[162:165], v247
	ds_read_b128 v[166:169], v247 offset:1024
	ds_read_b128 v[170:173], v247 offset:2048
	ds_read_b128 v[174:177], v247 offset:3072
	ds_read_b128 v[178:181], v247 offset:4096
	ds_read_b128 v[182:185], v247 offset:5120
	ds_read_b128 v[186:189], v247 offset:6144
	ds_read_b128 v[190:193], v247 offset:7168
	global_load_lds_dwordx4 v[210:211], off
	v_lshl_add_u64 v[210:211], s[48:49], 0, v[208:209]
	s_add_i32 m0, s92, 0xe000
	s_nop 0
	global_load_lds_dwordx4 v[210:211], off
	s_waitcnt vmcnt(8)
	s_waitcnt lgkmcnt(0)
	s_barrier
	s_setprio 1
	v_mfma_f32_16x16x32_bf16 v[126:129], v[146:149], v[162:165], v[126:129]
	v_mfma_f32_16x16x32_bf16 v[126:129], v[150:153], v[166:169], v[126:129]
	v_mfma_f32_16x16x32_bf16 v[102:105], v[146:149], v[170:173], v[102:105]
	v_mfma_f32_16x16x32_bf16 v[102:105], v[150:153], v[174:177], v[102:105]
	v_mfma_f32_16x16x32_bf16 v[86:89], v[146:149], v[178:181], v[86:89]
	v_mfma_f32_16x16x32_bf16 v[86:89], v[150:153], v[182:185], v[86:89]
	v_mfma_f32_16x16x32_bf16 v[70:73], v[146:149], v[186:189], v[70:73]
	v_mfma_f32_16x16x32_bf16 v[70:73], v[150:153], v[190:193], v[70:73]
	v_mfma_f32_16x16x32_bf16 v[122:125], v[154:157], v[162:165], v[122:125]
	v_mfma_f32_16x16x32_bf16 v[122:125], v[158:161], v[166:169], v[122:125]
	v_mfma_f32_16x16x32_bf16 v[98:101], v[154:157], v[170:173], v[98:101]
	v_mfma_f32_16x16x32_bf16 v[98:101], v[158:161], v[174:177], v[98:101]
	v_mfma_f32_16x16x32_bf16 v[82:85], v[154:157], v[178:181], v[82:85]
	v_mfma_f32_16x16x32_bf16 v[82:85], v[158:161], v[182:185], v[82:85]
	v_mfma_f32_16x16x32_bf16 v[66:69], v[154:157], v[186:189], v[66:69]
	v_mfma_f32_16x16x32_bf16 v[66:69], v[158:161], v[190:193], v[66:69]
	v_mfma_f32_16x16x32_bf16 v[130:133], v[110:113], v[162:165], v[130:133]
	v_mfma_f32_16x16x32_bf16 v[130:133], v[118:121], v[166:169], v[130:133]
	v_mfma_f32_16x16x32_bf16 v[114:117], v[110:113], v[170:173], v[114:117]
	v_mfma_f32_16x16x32_bf16 v[114:117], v[118:121], v[174:177], v[114:117]
	v_mfma_f32_16x16x32_bf16 v[94:97], v[110:113], v[178:181], v[94:97]
	v_mfma_f32_16x16x32_bf16 v[94:97], v[118:121], v[182:185], v[94:97]
	v_mfma_f32_16x16x32_bf16 v[78:81], v[110:113], v[186:189], v[78:81]
	v_mfma_f32_16x16x32_bf16 v[78:81], v[118:121], v[190:193], v[78:81]
	v_mfma_f32_16x16x32_bf16 v[134:137], v[138:141], v[162:165], v[134:137]
	v_mfma_f32_16x16x32_bf16 v[134:137], v[142:145], v[166:169], v[134:137]
	v_mfma_f32_16x16x32_bf16 v[106:109], v[138:141], v[170:173], v[106:109]
	v_mfma_f32_16x16x32_bf16 v[106:109], v[142:145], v[174:177], v[106:109]
	v_mfma_f32_16x16x32_bf16 v[90:93], v[138:141], v[178:181], v[90:93]
	v_mfma_f32_16x16x32_bf16 v[90:93], v[142:145], v[182:185], v[90:93]
	v_mfma_f32_16x16x32_bf16 v[74:77], v[138:141], v[186:189], v[74:77]
	v_mfma_f32_16x16x32_bf16 v[74:77], v[142:145], v[190:193], v[74:77]
	s_setprio 0
	s_barrier
	s_add_i32 vcc_hi, vcc_hi, s6
	v_lshl_add_u64 v[210:211], s[38:39], 0, v[0:1]
	s_mov_b32 m0, vcc_hi
	ds_read_b128 v[162:165], v247 offset:16384
	ds_read_b128 v[166:169], v247 offset:17408
	ds_read_b128 v[170:173], v247 offset:18432
	ds_read_b128 v[174:177], v247 offset:19456
	ds_read_b128 v[178:181], v247 offset:20480
	ds_read_b128 v[182:185], v247 offset:21504
	ds_read_b128 v[186:189], v247 offset:22528
	ds_read_b128 v[190:193], v247 offset:23552
	global_load_lds_dwordx4 v[210:211], off
	s_add_i32 m0, vcc_hi, 0x2000
	v_lshl_add_u64 v[212:213], s[38:39], 0, v[204:205]
	s_add_u32 s38, s38, s58
	s_addc_u32 s39, s39, 0
	s_add_i32 s18, s18, s6
	global_load_lds_dwordx4 v[212:213], off
	v_lshl_add_u64 v[214:215], s[38:39], 0, v[0:1]
	s_mov_b32 m0, s18
	v_lshl_add_u64 v[216:217], s[38:39], 0, v[204:205]
	global_load_lds_dwordx4 v[214:215], off
	s_add_i32 m0, s18, 0x2000
	v_lshl_add_u64 v[218:219], s[46:47], 0, v[194:195]
	global_load_lds_dwordx4 v[216:217], off
	s_mov_b32 m0, s92
	v_lshl_add_u64 v[220:221], s[46:47], 0, v[202:203]
	global_load_lds_dwordx4 v[218:219], off
	s_mov_b32 m0, s93
	s_nop 0
	global_load_lds_dwordx4 v[220:221], off
	s_waitcnt vmcnt(8)
	s_waitcnt lgkmcnt(0)
	s_barrier
; #define PG8_STAGE(bufoff, gbase, voff) do { _Pragma("unroll") for (int _i = 0; _i < 2; ++_i) \
;         __builtin_amdgcn_global_load_lds((const unsigned*)((const char*)(gbase) + (voff)[_i]), (PG8_LAS unsigned*)(lds + (bufoff) + ldsw + _i * 8192), 16, 0, 0); } while (0)
; #define PG8_LDA(dst, b, h) do { _Pragma("unroll") for (int m = 0; m < 4; ++m) _Pragma("unroll") for (int k = 0; k < 2; ++k) dst[m][k] = *(const PG8_LAS bf16x8*)(lds + PG8_SA(b, h) + aoff + m * 2048 + k * 1024); } while (0)
; #define PG8_LDB(dst, b, h) do { _Pragma("unroll") for (int n = 0; n < 2; ++n) _Pragma("unroll") for (int k = 0; k < 2; ++k) dst[n][k] = *(const PG8_LAS bf16x8*)(lds + PG8_SB(b, h) + boff + n * 2048 + k * 1024); } while (0)
; #define PG8_MMA(ai, bj, At, Bt) do { __builtin_amdgcn_s_setprio(1); _Pragma("unroll") for (int m = 0; m < 4; ++m) _Pragma("unroll") for (int n = 0; n < 2; ++n) _Pragma("unroll") for (int k = 0; k < 2; ++k) \
;         acc[ai][bj][m][n] = __builtin_amdgcn_mfma_f32_16x16x32_bf16(Bt[n][k], At[m][k], acc[ai][bj][m][n], 0, 0, 0); __builtin_amdgcn_s_setprio(0); } while (0)
; #define PG8_WAIT_V(n) asm volatile("s_waitcnt vmcnt(" #n ")" ::: "memory")
; #define PG8_WAIT_L(n) asm volatile("s_waitcnt lgkmcnt(" #n ")" ::: "memory")
; #define PG8_BAR __builtin_amdgcn_s_barrier()
; #define PG8_SCHED __builtin_amdgcn_sched_barrier(0)
; template <class Epi, class Sched, bool ALIGN_EPI = false, bool SP2 = false>
; __device__ __forceinline__ void gemm_phase(PG8_LAS unsigned char* lds, const Gemm g, const Sched& S, const Epi& E) {
;     ...
;             PG8_WAIT_V(8); PG8_WAIT_L(0); PG8_BAR; PG8_MMA(1, 0, At, B0); PG8_MMA(1, 1, At, B1); PG8_BAR; PG8_SCHED;
;             PG8_LDB(B0, 1, 0); PG8_LDB(B1, 1, 1); PG8_SCHED; PG8_LDA(At, 1, 0); PG8_STAGE(PG8_SA(0, 1), a2 + hstep, voffA);
;             PG8_WAIT_V(8); PG8_WAIT_L(0); PG8_BAR; PG8_MMA(0, 0, At, B0); PG8_MMA(0, 1, At, B1); PG8_BAR; PG8_SCHED;
	s_setprio 1
	v_mfma_f32_16x16x32_bf16 v[54:57], v[146:149], v[162:165], v[54:57]
	v_mfma_f32_16x16x32_bf16 v[54:57], v[150:153], v[166:169], v[54:57]
	v_mfma_f32_16x16x32_bf16 v[38:41], v[146:149], v[170:173], v[38:41]
	v_mfma_f32_16x16x32_bf16 v[38:41], v[150:153], v[174:177], v[38:41]
	v_mfma_f32_16x16x32_bf16 v[22:25], v[146:149], v[178:181], v[22:25]
	v_mfma_f32_16x16x32_bf16 v[22:25], v[150:153], v[182:185], v[22:25]
	v_mfma_f32_16x16x32_bf16 v[6:9], v[146:149], v[186:189], v[6:9]
	v_mfma_f32_16x16x32_bf16 v[6:9], v[150:153], v[190:193], v[6:9]
	v_mfma_f32_16x16x32_bf16 v[50:53], v[154:157], v[162:165], v[50:53]
	v_mfma_f32_16x16x32_bf16 v[50:53], v[158:161], v[166:169], v[50:53]
	v_mfma_f32_16x16x32_bf16 v[34:37], v[154:157], v[170:173], v[34:37]
	v_mfma_f32_16x16x32_bf16 v[34:37], v[158:161], v[174:177], v[34:37]
	v_mfma_f32_16x16x32_bf16 v[18:21], v[154:157], v[178:181], v[18:21]
	v_mfma_f32_16x16x32_bf16 v[18:21], v[158:161], v[182:185], v[18:21]
	v_mfma_f32_16x16x32_bf16 v[2:5], v[154:157], v[186:189], v[2:5]
	v_mfma_f32_16x16x32_bf16 v[2:5], v[158:161], v[190:193], v[2:5]
	v_mfma_f32_16x16x32_bf16 v[62:65], v[110:113], v[162:165], v[62:65]
	v_mfma_f32_16x16x32_bf16 v[62:65], v[118:121], v[166:169], v[62:65]
	v_mfma_f32_16x16x32_bf16 v[46:49], v[110:113], v[170:173], v[46:49]
	v_mfma_f32_16x16x32_bf16 v[46:49], v[118:121], v[174:177], v[46:49]
	v_mfma_f32_16x16x32_bf16 v[30:33], v[110:113], v[178:181], v[30:33]
	v_mfma_f32_16x16x32_bf16 v[30:33], v[118:121], v[182:185], v[30:33]
	v_mfma_f32_16x16x32_bf16 v[14:17], v[110:113], v[186:189], v[14:17]
	v_mfma_f32_16x16x32_bf16 v[14:17], v[118:121], v[190:193], v[14:17]
	v_mfma_f32_16x16x32_bf16 v[58:61], v[138:141], v[162:165], v[58:61]
	v_mfma_f32_16x16x32_bf16 v[58:61], v[142:145], v[166:169], v[58:61]
	v_mfma_f32_16x16x32_bf16 v[42:45], v[138:141], v[170:173], v[42:45]
	v_mfma_f32_16x16x32_bf16 v[42:45], v[142:145], v[174:177], v[42:45]
	v_mfma_f32_16x16x32_bf16 v[26:29], v[138:141], v[178:181], v[26:29]
	v_mfma_f32_16x16x32_bf16 v[26:29], v[142:145], v[182:185], v[26:29]
	v_mfma_f32_16x16x32_bf16 v[10:13], v[138:141], v[186:189], v[10:13]
	v_mfma_f32_16x16x32_bf16 v[10:13], v[142:145], v[190:193], v[10:13]
	s_setprio 0
	s_barrier
	s_add_i32 s18, 0, 0x18000
	s_add_i32 vcc_hi, 0, 0x1c000
	v_add_u32_e32 v142, s18, v245
	v_add_u32_e32 v158, vcc_hi, v245
	ds_read_b128 v[110:113], v142
	ds_read_b128 v[118:121], v142 offset:1024
	ds_read_b128 v[138:141], v142 offset:2048
	ds_read_b128 v[142:145], v142 offset:3072
	ds_read_b128 v[146:149], v158
	ds_read_b128 v[150:153], v158 offset:1024
	ds_read_b128 v[154:157], v158 offset:2048
	ds_read_b128 v[158:161], v158 offset:3072
	s_add_u32 s38, s46, s58
	s_addc_u32 s39, s47, 0
	s_mov_b32 m0, s94
	v_lshl_add_u64 v[222:223], s[38:39], 0, v[194:195]
	ds_read_b128 v[162:165], v247 offset:32768
	ds_read_b128 v[166:169], v247 offset:33792
	ds_read_b128 v[170:173], v247 offset:34816
	ds_read_b128 v[174:177], v247 offset:35840
	ds_read_b128 v[178:181], v247 offset:36864
	ds_read_b128 v[182:185], v247 offset:37888
	ds_read_b128 v[186:189], v247 offset:38912
	ds_read_b128 v[190:193], v247 offset:39936
	global_load_lds_dwordx4 v[222:223], off
	v_lshl_add_u64 v[222:223], s[38:39], 0, v[202:203]
	s_mov_b32 m0, s95
	s_nop 0
	global_load_lds_dwordx4 v[222:223], off
	s_waitcnt vmcnt(8)
	s_waitcnt lgkmcnt(0)
	s_barrier
	s_setprio 1
	v_mfma_f32_16x16x32_bf16 v[126:129], v[146:149], v[162:165], v[126:129]
	v_mfma_f32_16x16x32_bf16 v[126:129], v[150:153], v[166:169], v[126:129]
	v_mfma_f32_16x16x32_bf16 v[102:105], v[146:149], v[170:173], v[102:105]
	v_mfma_f32_16x16x32_bf16 v[102:105], v[150:153], v[174:177], v[102:105]
	v_mfma_f32_16x16x32_bf16 v[86:89], v[146:149], v[178:181], v[86:89]
	v_mfma_f32_16x16x32_bf16 v[86:89], v[150:153], v[182:185], v[86:89]
	v_mfma_f32_16x16x32_bf16 v[70:73], v[146:149], v[186:189], v[70:73]
	v_mfma_f32_16x16x32_bf16 v[70:73], v[150:153], v[190:193], v[70:73]
	v_mfma_f32_16x16x32_bf16 v[122:125], v[154:157], v[162:165], v[122:125]
	v_mfma_f32_16x16x32_bf16 v[122:125], v[158:161], v[166:169], v[122:125]
	v_mfma_f32_16x16x32_bf16 v[98:101], v[154:157], v[170:173], v[98:101]
	v_mfma_f32_16x16x32_bf16 v[98:101], v[158:161], v[174:177], v[98:101]
	v_mfma_f32_16x16x32_bf16 v[82:85], v[154:157], v[178:181], v[82:85]
	v_mfma_f32_16x16x32_bf16 v[82:85], v[158:161], v[182:185], v[82:85]
	v_mfma_f32_16x16x32_bf16 v[66:69], v[154:157], v[186:189], v[66:69]
	v_mfma_f32_16x16x32_bf16 v[66:69], v[158:161], v[190:193], v[66:69]
	v_mfma_f32_16x16x32_bf16 v[130:133], v[110:113], v[162:165], v[130:133]
	v_mfma_f32_16x16x32_bf16 v[130:133], v[118:121], v[166:169], v[130:133]
	v_mfma_f32_16x16x32_bf16 v[114:117], v[110:113], v[170:173], v[114:117]
	v_mfma_f32_16x16x32_bf16 v[114:117], v[118:121], v[174:177], v[114:117]
	v_mfma_f32_16x16x32_bf16 v[94:97], v[110:113], v[178:181], v[94:97]
	v_mfma_f32_16x16x32_bf16 v[94:97], v[118:121], v[182:185], v[94:97]
	v_mfma_f32_16x16x32_bf16 v[78:81], v[110:113], v[186:189], v[78:81]
	v_mfma_f32_16x16x32_bf16 v[78:81], v[118:121], v[190:193], v[78:81]
	v_mfma_f32_16x16x32_bf16 v[134:137], v[138:141], v[162:165], v[134:137]
	v_mfma_f32_16x16x32_bf16 v[134:137], v[142:145], v[166:169], v[134:137]
	v_mfma_f32_16x16x32_bf16 v[106:109], v[138:141], v[170:173], v[106:109]
	v_mfma_f32_16x16x32_bf16 v[106:109], v[142:145], v[174:177], v[106:109]
	v_mfma_f32_16x16x32_bf16 v[90:93], v[138:141], v[178:181], v[90:93]
	v_mfma_f32_16x16x32_bf16 v[90:93], v[142:145], v[182:185], v[90:93]
	v_mfma_f32_16x16x32_bf16 v[74:77], v[138:141], v[186:189], v[74:77]
	v_mfma_f32_16x16x32_bf16 v[74:77], v[142:145], v[190:193], v[74:77]
	s_setprio 0
	s_barrier
; #define PG8_STAGE(bufoff, gbase, voff) do { _Pragma("unroll") for (int _i = 0; _i < 2; ++_i) \
;         __builtin_amdgcn_global_load_lds((const unsigned*)((const char*)(gbase) + (voff)[_i]), (PG8_LAS unsigned*)(lds + (bufoff) + ldsw + _i * 8192), 16, 0, 0); } while (0)
; #define PG8_LDA(dst, b, h) do { _Pragma("unroll") for (int m = 0; m < 4; ++m) _Pragma("unroll") for (int k = 0; k < 2; ++k) dst[m][k] = *(const PG8_LAS bf16x8*)(lds + PG8_SA(b, h) + aoff + m * 2048 + k * 1024); } while (0)
; #define PG8_MMA(ai, bj, At, Bt) do { __builtin_amdgcn_s_setprio(1); _Pragma("unroll") for (int m = 0; m < 4; ++m) _Pragma("unroll") for (int n = 0; n < 2; ++n) _Pragma("unroll") for (int k = 0; k < 2; ++k) \
;         acc[ai][bj][m][n] = __builtin_amdgcn_mfma_f32_16x16x32_bf16(Bt[n][k], At[m][k], acc[ai][bj][m][n], 0, 0, 0); __builtin_amdgcn_s_setprio(0); } while (0)
; #define PG8_WAIT_V(n) asm volatile("s_waitcnt vmcnt(" #n ")" ::: "memory")
; #define PG8_WAIT_L(n) asm volatile("s_waitcnt lgkmcnt(" #n ")" ::: "memory")
; #define PG8_BAR __builtin_amdgcn_s_barrier()
; #define PG8_SCHED __builtin_amdgcn_sched_barrier(0)
; template <class Epi, class Sched, bool ALIGN_EPI = false, bool SP2 = false>
; __device__ __forceinline__ void gemm_phase(PG8_LAS unsigned char* lds, const Gemm g, const Sched& S, const Epi& E) {
;     ...
;         for (int t = 0; t < nt; t += 2) {
;             const bool last = (t == nt - 2);
;     ...
;             PG8_LDA(At, 1, 1); PG8_STAGE(PG8_SB(1, 0), b3, voffB); PG8_STAGE(PG8_SB(1, 1), b3 + hstep, voffB); PG8_STAGE(PG8_SA(1, 0), a3, voffA);
;             PG8_WAIT_V(8); PG8_WAIT_L(0); PG8_BAR; PG8_MMA(1, 0, At, B0); PG8_MMA(1, 1, At, B1); PG8_BAR; PG8_SCHED;
	s_add_i32 s18, s18, s6
	v_lshl_add_u64 v[210:211], v[210:211], 0, s[30:31]
	s_mov_b32 m0, s18
	ds_read_b128 v[162:165], v247 offset:49152
	ds_read_b128 v[166:169], v247 offset:50176
	ds_read_b128 v[170:173], v247 offset:51200
	ds_read_b128 v[174:177], v247 offset:52224
	ds_read_b128 v[178:181], v247 offset:53248
	ds_read_b128 v[182:185], v247 offset:54272
	ds_read_b128 v[186:189], v247 offset:55296
	ds_read_b128 v[190:193], v247 offset:56320
	global_load_lds_dwordx4 v[210:211], off
	v_lshl_add_u64 v[210:211], v[212:213], 0, s[30:31]
	s_add_i32 m0, s18, 0x2000
	s_add_i32 s18, vcc_hi, s6
	global_load_lds_dwordx4 v[210:211], off
	v_lshl_add_u64 v[210:211], v[214:215], 0, s[30:31]
	s_mov_b32 m0, s18
	s_nop 0
	global_load_lds_dwordx4 v[210:211], off
	v_lshl_add_u64 v[210:211], v[216:217], 0, s[30:31]
	s_add_i32 m0, s18, 0x2000
	s_nop 0
	global_load_lds_dwordx4 v[210:211], off
	v_lshl_add_u64 v[210:211], v[218:219], 0, s[30:31]
	s_mov_b32 m0, s97
	s_nop 0
	global_load_lds_dwordx4 v[210:211], off
	v_lshl_add_u64 v[210:211], v[220:221], 0, s[30:31]
	s_mov_b32 m0, s98
	s_nop 0
	global_load_lds_dwordx4 v[210:211], off
	s_waitcnt vmcnt(8)
	s_waitcnt lgkmcnt(0)
	s_barrier
	s_setprio 1
	v_mfma_f32_16x16x32_bf16 v[54:57], v[146:149], v[162:165], v[54:57]
	v_mfma_f32_16x16x32_bf16 v[54:57], v[150:153], v[166:169], v[54:57]
	v_mfma_f32_16x16x32_bf16 v[38:41], v[146:149], v[170:173], v[38:41]
	v_mfma_f32_16x16x32_bf16 v[38:41], v[150:153], v[174:177], v[38:41]
	v_mfma_f32_16x16x32_bf16 v[22:25], v[146:149], v[178:181], v[22:25]
	v_mfma_f32_16x16x32_bf16 v[22:25], v[150:153], v[182:185], v[22:25]
	v_mfma_f32_16x16x32_bf16 v[6:9], v[146:149], v[186:189], v[6:9]
	v_mfma_f32_16x16x32_bf16 v[6:9], v[150:153], v[190:193], v[6:9]
	v_mfma_f32_16x16x32_bf16 v[50:53], v[154:157], v[162:165], v[50:53]
	v_mfma_f32_16x16x32_bf16 v[50:53], v[158:161], v[166:169], v[50:53]
	v_mfma_f32_16x16x32_bf16 v[34:37], v[154:157], v[170:173], v[34:37]
	v_mfma_f32_16x16x32_bf16 v[34:37], v[158:161], v[174:177], v[34:37]
	v_mfma_f32_16x16x32_bf16 v[18:21], v[154:157], v[178:181], v[18:21]
	v_mfma_f32_16x16x32_bf16 v[18:21], v[158:161], v[182:185], v[18:21]
	v_mfma_f32_16x16x32_bf16 v[2:5], v[154:157], v[186:189], v[2:5]
	v_mfma_f32_16x16x32_bf16 v[2:5], v[158:161], v[190:193], v[2:5]
	v_mfma_f32_16x16x32_bf16 v[62:65], v[110:113], v[162:165], v[62:65]
	v_mfma_f32_16x16x32_bf16 v[62:65], v[118:121], v[166:169], v[62:65]
	v_mfma_f32_16x16x32_bf16 v[46:49], v[110:113], v[170:173], v[46:49]
	v_mfma_f32_16x16x32_bf16 v[46:49], v[118:121], v[174:177], v[46:49]
	v_mfma_f32_16x16x32_bf16 v[30:33], v[110:113], v[178:181], v[30:33]
	v_mfma_f32_16x16x32_bf16 v[30:33], v[118:121], v[182:185], v[30:33]
	v_mfma_f32_16x16x32_bf16 v[14:17], v[110:113], v[186:189], v[14:17]
	v_mfma_f32_16x16x32_bf16 v[14:17], v[118:121], v[190:193], v[14:17]
	v_mfma_f32_16x16x32_bf16 v[58:61], v[138:141], v[162:165], v[58:61]
	v_mfma_f32_16x16x32_bf16 v[58:61], v[142:145], v[166:169], v[58:61]
	v_mfma_f32_16x16x32_bf16 v[42:45], v[138:141], v[170:173], v[42:45]
	v_mfma_f32_16x16x32_bf16 v[42:45], v[142:145], v[174:177], v[42:45]
	v_mfma_f32_16x16x32_bf16 v[26:29], v[138:141], v[178:181], v[26:29]
	v_mfma_f32_16x16x32_bf16 v[26:29], v[142:145], v[182:185], v[26:29]
	v_mfma_f32_16x16x32_bf16 v[10:13], v[138:141], v[186:189], v[10:13]
	v_mfma_f32_16x16x32_bf16 v[10:13], v[142:145], v[190:193], v[10:13]
	s_setprio 0
	s_barrier
	s_add_u32 s48, s48, 0x100
	s_addc_u32 s49, s49, 0
	s_add_u32 s50, s50, 0x100
	s_addc_u32 s51, s51, 0
	s_cmp_ge_u32 vcc_lo, s96
	s_mov_b32 s46, vcc_lo
	s_cbranch_scc0 .LBB0_274
	s_and_b64 vcc, exec, s[72:73]
	s_cbranch_vccz .LBB0_277
	s_barrier

; #define PG8_STAGE(bufoff, gbase, voff) do { _Pragma("unroll") for (int _i = 0; _i < 2; ++_i) \
;         __builtin_amdgcn_global_load_lds((const unsigned*)((const char*)(gbase) + (voff)[_i]), (PG8_LAS unsigned*)(lds + (bufoff) + ldsw + _i * 8192), 16, 0, 0); } while (0)
; #define PG8_LDA(dst, b, h) do { _Pragma("unroll") for (int m = 0; m < 4; ++m) _Pragma("unroll") for (int k = 0; k < 2; ++k) dst[m][k] = *(const PG8_LAS bf16x8*)(lds + PG8_SA(b, h) + aoff + m * 2048 + k * 1024); } while (0)
; #define PG8_LDB(dst, b, h) do { _Pragma("unroll") for (int n = 0; n < 2; ++n) _Pragma("unroll") for (int k = 0; k < 2; ++k) dst[n][k] = *(const PG8_LAS bf16x8*)(lds + PG8_SB(b, h) + boff + n * 2048 + k * 1024); } while (0)
; #define PG8_MMA(ai, bj, At, Bt) do { __builtin_amdgcn_s_setprio(1); _Pragma("unroll") for (int m = 0; m < 4; ++m) _Pragma("unroll") for (int n = 0; n < 2; ++n) _Pragma("unroll") for (int k = 0; k < 2; ++k) \
;         acc[ai][bj][m][n] = __builtin_amdgcn_mfma_f32_16x16x32_bf16(Bt[n][k], At[m][k], acc[ai][bj][m][n], 0, 0, 0); __builtin_amdgcn_s_setprio(0); } while (0)
; #define PG8_WAIT_V(n) asm volatile("s_waitcnt vmcnt(" #n ")" ::: "memory")
; #define PG8_WAIT_L(n) asm volatile("s_waitcnt lgkmcnt(" #n ")" ::: "memory")
; #define PG8_BAR __builtin_amdgcn_s_barrier()
; template <class Epi, class Sched, bool ALIGN_EPI = false, bool SP2 = false>
; __device__ __forceinline__ void gemm_phase(PG8_LAS unsigned char* lds, const Gemm g, const Sched& S, const Epi& E) {
;     ...
;             const char* a1 = cA + (size_t)(t + 1) * kstep;
;             const char* a2 = last ? nA : cA + (size_t)(t + 2) * kstep; const char* b2 = last ? nB : cB + (size_t)(t + 2) * kstep;
;             const char* a3 = a2 + kstep; const char* b3 = b2 + kstep;
;             if (last && has_next) S.a_ready(nxt);
;             if constexpr (SP2) {
;             PG8_LDB(B0, 0, 0); PG8_LDB(B1, 0, 1); PG8_SCHED; PG8_LDA(At, 0, 0); PG8_STAGE(PG8_SA(1, 1), a1 + hstep, voffA);
;             PG8_WAIT_V(8); PG8_WAIT_L(0); PG8_BAR; PG8_MMA(0, 0, At, B0); PG8_MMA(0, 1, At, B1); PG8_BAR; PG8_SCHED;
;             PG8_LDA(At, 0, 1); PG8_STAGE(PG8_SB(0, 0), b2, voffB); PG8_STAGE(PG8_SB(0, 1), b2 + hstep, voffB); PG8_STAGE(PG8_SA(0, 0), a2, voffA);
;             PG8_WAIT_V(8); PG8_WAIT_L(0); PG8_BAR; PG8_MMA(1, 0, At, B0); PG8_MMA(1, 1, At, B1); PG8_BAR; PG8_SCHED;
.LBB0_408:
	s_add_u32 s38, s48, 0xfffc0080
	s_addc_u32 s39, s49, -1
	s_add_i32 s85, 0, 0x10000
	s_cmp_eq_u32 s84, 12
	s_cselect_b32 s73, s21, s39
	s_cselect_b32 s72, s27, s38
	v_add_u32_e32 v0, s85, v167
	s_cselect_b32 s47, s29, s69
	s_cselect_b32 s46, s33, s53
	s_add_i32 s38, 0, 0x14000
	ds_read_b128 v[142:145], v0
	ds_read_b128 v[146:149], v0 offset:1024
	ds_read_b128 v[150:153], v0 offset:2048
	ds_read_b128 v[154:157], v0 offset:3072
	v_add_u32_e32 v0, s38, v167
	ds_read_b128 v[158:161], v0
	ds_read_b128 v[162:165], v0 offset:1024
	ds_read_b128 v[172:175], v0 offset:2048
	ds_read_b128 v[176:179], v0 offset:3072
	v_lshl_add_u64 v[218:219], s[48:49], 0, v[138:139]
	s_add_i32 m0, s76, 0xc000
	ds_read_b128 v[180:183], v170
	ds_read_b128 v[184:187], v170 offset:1024
	ds_read_b128 v[188:191], v170 offset:2048
	ds_read_b128 v[192:195], v170 offset:3072
	ds_read_b128 v[202:205], v170 offset:4096
	ds_read_b128 v[206:209], v170 offset:5120
	ds_read_b128 v[210:213], v170 offset:6144
	ds_read_b128 v[214:217], v170 offset:7168
	global_load_lds_dwordx4 v[218:219], off
	v_lshl_add_u64 v[218:219], s[48:49], 0, v[140:141]
	s_add_i32 m0, s76, 0xe000
	s_nop 0
	global_load_lds_dwordx4 v[218:219], off
	s_waitcnt vmcnt(8)
	s_waitcnt lgkmcnt(0)
	s_barrier
	s_setprio 1
	v_mfma_f32_16x16x32_bf16 v[114:117], v[158:161], v[180:183], v[114:117]
	v_mfma_f32_16x16x32_bf16 v[114:117], v[162:165], v[184:187], v[114:117]
	v_mfma_f32_16x16x32_bf16 v[98:101], v[158:161], v[188:191], v[98:101]
	v_mfma_f32_16x16x32_bf16 v[98:101], v[162:165], v[192:195], v[98:101]
	v_mfma_f32_16x16x32_bf16 v[82:85], v[158:161], v[202:205], v[82:85]
	v_mfma_f32_16x16x32_bf16 v[82:85], v[162:165], v[206:209], v[82:85]
	v_mfma_f32_16x16x32_bf16 v[66:69], v[158:161], v[210:213], v[66:69]
	v_mfma_f32_16x16x32_bf16 v[66:69], v[162:165], v[214:217], v[66:69]
	v_mfma_f32_16x16x32_bf16 v[118:121], v[172:175], v[180:183], v[118:121]
	v_mfma_f32_16x16x32_bf16 v[118:121], v[176:179], v[184:187], v[118:121]
	v_mfma_f32_16x16x32_bf16 v[102:105], v[172:175], v[188:191], v[102:105]
	v_mfma_f32_16x16x32_bf16 v[102:105], v[176:179], v[192:195], v[102:105]
	v_mfma_f32_16x16x32_bf16 v[86:89], v[172:175], v[202:205], v[86:89]
	v_mfma_f32_16x16x32_bf16 v[86:89], v[176:179], v[206:209], v[86:89]
	v_mfma_f32_16x16x32_bf16 v[70:73], v[172:175], v[210:213], v[70:73]
	v_mfma_f32_16x16x32_bf16 v[70:73], v[176:179], v[214:217], v[70:73]
	v_mfma_f32_16x16x32_bf16 v[122:125], v[142:145], v[180:183], v[122:125]
	v_mfma_f32_16x16x32_bf16 v[122:125], v[146:149], v[184:187], v[122:125]
	v_mfma_f32_16x16x32_bf16 v[106:109], v[142:145], v[188:191], v[106:109]
	v_mfma_f32_16x16x32_bf16 v[106:109], v[146:149], v[192:195], v[106:109]
	v_mfma_f32_16x16x32_bf16 v[90:93], v[142:145], v[202:205], v[90:93]
	v_mfma_f32_16x16x32_bf16 v[90:93], v[146:149], v[206:209], v[90:93]
	v_mfma_f32_16x16x32_bf16 v[74:77], v[142:145], v[210:213], v[74:77]
	v_mfma_f32_16x16x32_bf16 v[74:77], v[146:149], v[214:217], v[74:77]
	v_mfma_f32_16x16x32_bf16 v[126:129], v[150:153], v[180:183], v[126:129]
	v_mfma_f32_16x16x32_bf16 v[126:129], v[154:157], v[184:187], v[126:129]
	v_mfma_f32_16x16x32_bf16 v[110:113], v[150:153], v[188:191], v[110:113]
	v_mfma_f32_16x16x32_bf16 v[110:113], v[154:157], v[192:195], v[110:113]
	v_mfma_f32_16x16x32_bf16 v[94:97], v[150:153], v[202:205], v[94:97]
	v_mfma_f32_16x16x32_bf16 v[94:97], v[154:157], v[206:209], v[94:97]
	v_mfma_f32_16x16x32_bf16 v[78:81], v[150:153], v[210:213], v[78:81]
	v_mfma_f32_16x16x32_bf16 v[78:81], v[154:157], v[214:217], v[78:81]
	s_setprio 0
	s_barrier
	s_add_i32 s39, s85, s75
	v_lshl_add_u64 v[218:219], s[46:47], 0, v[134:135]
	s_mov_b32 m0, s39
	ds_read_b128 v[180:183], v170 offset:16384
	ds_read_b128 v[184:187], v170 offset:17408
	ds_read_b128 v[188:191], v170 offset:18432
	ds_read_b128 v[192:195], v170 offset:19456
	ds_read_b128 v[202:205], v170 offset:20480
	ds_read_b128 v[206:209], v170 offset:21504
	ds_read_b128 v[210:213], v170 offset:22528
	ds_read_b128 v[214:217], v170 offset:23552
	global_load_lds_dwordx4 v[218:219], off
	s_add_i32 m0, s39, 0x2000
	s_add_u32 s92, s46, 0x40000
	v_lshl_add_u64 v[220:221], s[46:47], 0, v[130:131]
	s_addc_u32 s93, s47, 0
	s_add_i32 s38, s38, s75
	global_load_lds_dwordx4 v[220:221], off
	v_lshl_add_u64 v[222:223], s[92:93], 0, v[134:135]
	s_mov_b32 m0, s38
	v_lshl_add_u64 v[224:225], s[72:73], 0, v[132:133]
	global_load_lds_dwordx4 v[222:223], off
	v_lshl_add_u64 v[222:223], s[92:93], 0, v[130:131]
	s_add_i32 m0, s38, 0x2000
	s_nop 0
	global_load_lds_dwordx4 v[222:223], off
	v_lshl_add_u64 v[222:223], s[72:73], 0, v[136:137]
	s_mov_b32 m0, s76
	s_nop 0
	global_load_lds_dwordx4 v[222:223], off
	s_mov_b32 m0, s77
	s_nop 0
	global_load_lds_dwordx4 v[224:225], off
	s_waitcnt vmcnt(8)
	s_waitcnt lgkmcnt(0)
	s_barrier
; #define PG8_STAGE(bufoff, gbase, voff) do { _Pragma("unroll") for (int _i = 0; _i < 2; ++_i) \
;         __builtin_amdgcn_global_load_lds((const unsigned*)((const char*)(gbase) + (voff)[_i]), (PG8_LAS unsigned*)(lds + (bufoff) + ldsw + _i * 8192), 16, 0, 0); } while (0)
; #define PG8_LDA(dst, b, h) do { _Pragma("unroll") for (int m = 0; m < 4; ++m) _Pragma("unroll") for (int k = 0; k < 2; ++k) dst[m][k] = *(const PG8_LAS bf16x8*)(lds + PG8_SA(b, h) + aoff + m * 2048 + k * 1024); } while (0)
; #define PG8_LDB(dst, b, h) do { _Pragma("unroll") for (int n = 0; n < 2; ++n) _Pragma("unroll") for (int k = 0; k < 2; ++k) dst[n][k] = *(const PG8_LAS bf16x8*)(lds + PG8_SB(b, h) + boff + n * 2048 + k * 1024); } while (0)
; #define PG8_MMA(ai, bj, At, Bt) do { __builtin_amdgcn_s_setprio(1); _Pragma("unroll") for (int m = 0; m < 4; ++m) _Pragma("unroll") for (int n = 0; n < 2; ++n) _Pragma("unroll") for (int k = 0; k < 2; ++k) \
;         acc[ai][bj][m][n] = __builtin_amdgcn_mfma_f32_16x16x32_bf16(Bt[n][k], At[m][k], acc[ai][bj][m][n], 0, 0, 0); __builtin_amdgcn_s_setprio(0); } while (0)
; #define PG8_WAIT_V(n) asm volatile("s_waitcnt vmcnt(" #n ")" ::: "memory")
; #define PG8_WAIT_L(n) asm volatile("s_waitcnt lgkmcnt(" #n ")" ::: "memory")
; #define PG8_BAR __builtin_amdgcn_s_barrier()
; #define PG8_SCHED __builtin_amdgcn_sched_barrier(0)
; template <class Epi, class Sched, bool ALIGN_EPI = false, bool SP2 = false>
; __device__ __forceinline__ void gemm_phase(PG8_LAS unsigned char* lds, const Gemm g, const Sched& S, const Epi& E) {
;     ...
;             PG8_WAIT_V(8); PG8_WAIT_L(0); PG8_BAR; PG8_MMA(1, 0, At, B0); PG8_MMA(1, 1, At, B1); PG8_BAR; PG8_SCHED;
;             PG8_LDB(B0, 1, 0); PG8_LDB(B1, 1, 1); PG8_SCHED; PG8_LDA(At, 1, 0); PG8_STAGE(PG8_SA(0, 1), a2 + hstep, voffA);
;             PG8_WAIT_V(8); PG8_WAIT_L(0); PG8_BAR; PG8_MMA(0, 0, At, B0); PG8_MMA(0, 1, At, B1); PG8_BAR; PG8_SCHED;
	s_setprio 1
	v_mfma_f32_16x16x32_bf16 v[50:53], v[158:161], v[180:183], v[50:53]
	v_mfma_f32_16x16x32_bf16 v[50:53], v[162:165], v[184:187], v[50:53]
	v_mfma_f32_16x16x32_bf16 v[34:37], v[158:161], v[188:191], v[34:37]
	v_mfma_f32_16x16x32_bf16 v[34:37], v[162:165], v[192:195], v[34:37]
	v_mfma_f32_16x16x32_bf16 v[18:21], v[158:161], v[202:205], v[18:21]
	v_mfma_f32_16x16x32_bf16 v[18:21], v[162:165], v[206:209], v[18:21]
	v_mfma_f32_16x16x32_bf16 v[2:5], v[158:161], v[210:213], v[2:5]
	v_mfma_f32_16x16x32_bf16 v[2:5], v[162:165], v[214:217], v[2:5]
	v_mfma_f32_16x16x32_bf16 v[54:57], v[172:175], v[180:183], v[54:57]
	v_mfma_f32_16x16x32_bf16 v[54:57], v[176:179], v[184:187], v[54:57]
	v_mfma_f32_16x16x32_bf16 v[38:41], v[172:175], v[188:191], v[38:41]
	v_mfma_f32_16x16x32_bf16 v[38:41], v[176:179], v[192:195], v[38:41]
	v_mfma_f32_16x16x32_bf16 v[22:25], v[172:175], v[202:205], v[22:25]
	v_mfma_f32_16x16x32_bf16 v[22:25], v[176:179], v[206:209], v[22:25]
	v_mfma_f32_16x16x32_bf16 v[6:9], v[172:175], v[210:213], v[6:9]
	v_mfma_f32_16x16x32_bf16 v[6:9], v[176:179], v[214:217], v[6:9]
	v_mfma_f32_16x16x32_bf16 v[58:61], v[142:145], v[180:183], v[58:61]
	v_mfma_f32_16x16x32_bf16 v[58:61], v[146:149], v[184:187], v[58:61]
	v_mfma_f32_16x16x32_bf16 v[42:45], v[142:145], v[188:191], v[42:45]
	v_mfma_f32_16x16x32_bf16 v[42:45], v[146:149], v[192:195], v[42:45]
	v_mfma_f32_16x16x32_bf16 v[26:29], v[142:145], v[202:205], v[26:29]
	v_mfma_f32_16x16x32_bf16 v[26:29], v[146:149], v[206:209], v[26:29]
	v_mfma_f32_16x16x32_bf16 v[10:13], v[142:145], v[210:213], v[10:13]
	v_mfma_f32_16x16x32_bf16 v[10:13], v[146:149], v[214:217], v[10:13]
	v_mfma_f32_16x16x32_bf16 v[62:65], v[150:153], v[180:183], v[62:65]
	v_mfma_f32_16x16x32_bf16 v[62:65], v[154:157], v[184:187], v[62:65]
	v_mfma_f32_16x16x32_bf16 v[46:49], v[150:153], v[188:191], v[46:49]
	v_mfma_f32_16x16x32_bf16 v[46:49], v[154:157], v[192:195], v[46:49]
	v_mfma_f32_16x16x32_bf16 v[30:33], v[150:153], v[202:205], v[30:33]
	v_mfma_f32_16x16x32_bf16 v[30:33], v[154:157], v[206:209], v[30:33]
	v_mfma_f32_16x16x32_bf16 v[14:17], v[150:153], v[210:213], v[14:17]
	v_mfma_f32_16x16x32_bf16 v[14:17], v[154:157], v[214:217], v[14:17]
	s_setprio 0
	s_barrier
	s_add_i32 s38, 0, 0x18000
	v_add_u32_e32 v0, s38, v167
	s_add_i32 s39, 0, 0x1c000
	ds_read_b128 v[142:145], v0
	ds_read_b128 v[146:149], v0 offset:1024
	ds_read_b128 v[150:153], v0 offset:2048
	ds_read_b128 v[154:157], v0 offset:3072
	v_add_u32_e32 v0, s39, v167
	ds_read_b128 v[158:161], v0
	ds_read_b128 v[162:165], v0 offset:1024
	ds_read_b128 v[172:175], v0 offset:2048
	ds_read_b128 v[176:179], v0 offset:3072
	s_add_u32 s72, s72, 0x40000
	s_addc_u32 s73, s73, 0
	s_mov_b32 m0, s78
	v_lshl_add_u64 v[226:227], s[72:73], 0, v[136:137]
	ds_read_b128 v[180:183], v170 offset:32768
	ds_read_b128 v[184:187], v170 offset:33792
	ds_read_b128 v[188:191], v170 offset:34816
	ds_read_b128 v[192:195], v170 offset:35840
	ds_read_b128 v[202:205], v170 offset:36864
	ds_read_b128 v[206:209], v170 offset:37888
	ds_read_b128 v[210:213], v170 offset:38912
	ds_read_b128 v[214:217], v170 offset:39936
	global_load_lds_dwordx4 v[226:227], off
	v_lshl_add_u64 v[226:227], s[72:73], 0, v[132:133]
	s_mov_b32 m0, s79
	s_nop 0
	global_load_lds_dwordx4 v[226:227], off
	s_waitcnt vmcnt(8)
	s_waitcnt lgkmcnt(0)
	s_barrier
	s_setprio 1
	v_mfma_f32_16x16x32_bf16 v[114:117], v[158:161], v[180:183], v[114:117]
	v_mfma_f32_16x16x32_bf16 v[114:117], v[162:165], v[184:187], v[114:117]
	v_mfma_f32_16x16x32_bf16 v[98:101], v[158:161], v[188:191], v[98:101]
	v_mfma_f32_16x16x32_bf16 v[98:101], v[162:165], v[192:195], v[98:101]
	v_mfma_f32_16x16x32_bf16 v[82:85], v[158:161], v[202:205], v[82:85]
	v_mfma_f32_16x16x32_bf16 v[82:85], v[162:165], v[206:209], v[82:85]
	v_mfma_f32_16x16x32_bf16 v[66:69], v[158:161], v[210:213], v[66:69]
	v_mfma_f32_16x16x32_bf16 v[66:69], v[162:165], v[214:217], v[66:69]
	v_mfma_f32_16x16x32_bf16 v[118:121], v[172:175], v[180:183], v[118:121]
	v_mfma_f32_16x16x32_bf16 v[118:121], v[176:179], v[184:187], v[118:121]
	v_mfma_f32_16x16x32_bf16 v[102:105], v[172:175], v[188:191], v[102:105]
	v_mfma_f32_16x16x32_bf16 v[102:105], v[176:179], v[192:195], v[102:105]
	v_mfma_f32_16x16x32_bf16 v[86:89], v[172:175], v[202:205], v[86:89]
	v_mfma_f32_16x16x32_bf16 v[86:89], v[176:179], v[206:209], v[86:89]
	v_mfma_f32_16x16x32_bf16 v[70:73], v[172:175], v[210:213], v[70:73]
	v_mfma_f32_16x16x32_bf16 v[70:73], v[176:179], v[214:217], v[70:73]
	v_mfma_f32_16x16x32_bf16 v[122:125], v[142:145], v[180:183], v[122:125]
	v_mfma_f32_16x16x32_bf16 v[122:125], v[146:149], v[184:187], v[122:125]
	v_mfma_f32_16x16x32_bf16 v[106:109], v[142:145], v[188:191], v[106:109]
	v_mfma_f32_16x16x32_bf16 v[106:109], v[146:149], v[192:195], v[106:109]
	v_mfma_f32_16x16x32_bf16 v[90:93], v[142:145], v[202:205], v[90:93]
	v_mfma_f32_16x16x32_bf16 v[90:93], v[146:149], v[206:209], v[90:93]
	v_mfma_f32_16x16x32_bf16 v[74:77], v[142:145], v[210:213], v[74:77]
	v_mfma_f32_16x16x32_bf16 v[74:77], v[146:149], v[214:217], v[74:77]
	v_mfma_f32_16x16x32_bf16 v[126:129], v[150:153], v[180:183], v[126:129]
	v_mfma_f32_16x16x32_bf16 v[126:129], v[154:157], v[184:187], v[126:129]
	v_mfma_f32_16x16x32_bf16 v[110:113], v[150:153], v[188:191], v[110:113]
	v_mfma_f32_16x16x32_bf16 v[110:113], v[154:157], v[192:195], v[110:113]
	v_mfma_f32_16x16x32_bf16 v[94:97], v[150:153], v[202:205], v[94:97]
	v_mfma_f32_16x16x32_bf16 v[94:97], v[154:157], v[206:209], v[94:97]
	v_mfma_f32_16x16x32_bf16 v[78:81], v[150:153], v[210:213], v[78:81]
	v_mfma_f32_16x16x32_bf16 v[78:81], v[154:157], v[214:217], v[78:81]
	s_setprio 0
	s_barrier
; #define PG8_STAGE(bufoff, gbase, voff) do { _Pragma("unroll") for (int _i = 0; _i < 2; ++_i) \
;         __builtin_amdgcn_global_load_lds((const unsigned*)((const char*)(gbase) + (voff)[_i]), (PG8_LAS unsigned*)(lds + (bufoff) + ldsw + _i * 8192), 16, 0, 0); } while (0)
; #define PG8_LDA(dst, b, h) do { _Pragma("unroll") for (int m = 0; m < 4; ++m) _Pragma("unroll") for (int k = 0; k < 2; ++k) dst[m][k] = *(const PG8_LAS bf16x8*)(lds + PG8_SA(b, h) + aoff + m * 2048 + k * 1024); } while (0)
; #define PG8_MMA(ai, bj, At, Bt) do { __builtin_amdgcn_s_setprio(1); _Pragma("unroll") for (int m = 0; m < 4; ++m) _Pragma("unroll") for (int n = 0; n < 2; ++n) _Pragma("unroll") for (int k = 0; k < 2; ++k) \
;         acc[ai][bj][m][n] = __builtin_amdgcn_mfma_f32_16x16x32_bf16(Bt[n][k], At[m][k], acc[ai][bj][m][n], 0, 0, 0); __builtin_amdgcn_s_setprio(0); } while (0)
; #define PG8_WAIT_V(n) asm volatile("s_waitcnt vmcnt(" #n ")" ::: "memory")
; #define PG8_WAIT_L(n) asm volatile("s_waitcnt lgkmcnt(" #n ")" ::: "memory")
; #define PG8_BAR __builtin_amdgcn_s_barrier()
; #define PG8_SCHED __builtin_amdgcn_sched_barrier(0)
; template <class Epi, class Sched, bool ALIGN_EPI = false, bool SP2 = false>
; __device__ __forceinline__ void gemm_phase(PG8_LAS unsigned char* lds, const Gemm g, const Sched& S, const Epi& E) {
;     ...
;         for (int t = 0; t < nt; t += 2) {
;             const bool last = (t == nt - 2);
;     ...
;             PG8_LDA(At, 1, 1); PG8_STAGE(PG8_SB(1, 0), b3, voffB); PG8_STAGE(PG8_SB(1, 1), b3 + hstep, voffB); PG8_STAGE(PG8_SA(1, 0), a3, voffA);
;             PG8_WAIT_V(8); PG8_WAIT_L(0); PG8_BAR; PG8_MMA(1, 0, At, B0); PG8_MMA(1, 1, At, B1); PG8_BAR; PG8_SCHED;
	s_add_i32 s38, s38, s75
	v_lshl_add_u64 v[218:219], v[218:219], 0, s[30:31]
	s_mov_b32 m0, s38
	ds_read_b128 v[180:183], v170 offset:49152
	ds_read_b128 v[184:187], v170 offset:50176
	ds_read_b128 v[188:191], v170 offset:51200
	ds_read_b128 v[192:195], v170 offset:52224
	ds_read_b128 v[202:205], v170 offset:53248
	ds_read_b128 v[206:209], v170 offset:54272
	ds_read_b128 v[210:213], v170 offset:55296
	ds_read_b128 v[214:217], v170 offset:56320
	global_load_lds_dwordx4 v[218:219], off
	s_add_i32 m0, s38, 0x2000
	s_add_u32 s46, s46, 0x40080
	v_lshl_add_u64 v[218:219], v[220:221], 0, s[30:31]
	s_addc_u32 s47, s47, 0
	s_add_i32 s38, s39, s75
	global_load_lds_dwordx4 v[218:219], off
	v_lshl_add_u64 v[218:219], s[46:47], 0, v[134:135]
	s_mov_b32 m0, s38
	s_nop 0
	global_load_lds_dwordx4 v[218:219], off
	v_lshl_add_u64 v[218:219], s[46:47], 0, v[130:131]
	s_add_i32 m0, s38, 0x2000
	s_nop 0
	global_load_lds_dwordx4 v[218:219], off
	v_lshl_add_u64 v[218:219], v[222:223], 0, s[30:31]
	s_mov_b32 m0, s80
	s_nop 0
	global_load_lds_dwordx4 v[218:219], off
	v_lshl_add_u64 v[218:219], v[224:225], 0, s[30:31]
	s_mov_b32 m0, s81
	s_nop 0
	global_load_lds_dwordx4 v[218:219], off
	s_waitcnt vmcnt(8)
	s_waitcnt lgkmcnt(0)
	s_barrier
	s_setprio 1
	v_mfma_f32_16x16x32_bf16 v[50:53], v[158:161], v[180:183], v[50:53]
	v_mfma_f32_16x16x32_bf16 v[50:53], v[162:165], v[184:187], v[50:53]
	v_mfma_f32_16x16x32_bf16 v[34:37], v[158:161], v[188:191], v[34:37]
	v_mfma_f32_16x16x32_bf16 v[34:37], v[162:165], v[192:195], v[34:37]
	v_mfma_f32_16x16x32_bf16 v[18:21], v[158:161], v[202:205], v[18:21]
	v_mfma_f32_16x16x32_bf16 v[18:21], v[162:165], v[206:209], v[18:21]
	v_mfma_f32_16x16x32_bf16 v[2:5], v[158:161], v[210:213], v[2:5]
	v_mfma_f32_16x16x32_bf16 v[2:5], v[162:165], v[214:217], v[2:5]
	v_mfma_f32_16x16x32_bf16 v[54:57], v[172:175], v[180:183], v[54:57]
	v_mfma_f32_16x16x32_bf16 v[54:57], v[176:179], v[184:187], v[54:57]
	v_mfma_f32_16x16x32_bf16 v[38:41], v[172:175], v[188:191], v[38:41]
	v_mfma_f32_16x16x32_bf16 v[38:41], v[176:179], v[192:195], v[38:41]
	v_mfma_f32_16x16x32_bf16 v[22:25], v[172:175], v[202:205], v[22:25]
	v_mfma_f32_16x16x32_bf16 v[22:25], v[176:179], v[206:209], v[22:25]
	v_mfma_f32_16x16x32_bf16 v[6:9], v[172:175], v[210:213], v[6:9]
	v_mfma_f32_16x16x32_bf16 v[6:9], v[176:179], v[214:217], v[6:9]
	v_mfma_f32_16x16x32_bf16 v[58:61], v[142:145], v[180:183], v[58:61]
	v_mfma_f32_16x16x32_bf16 v[58:61], v[146:149], v[184:187], v[58:61]
	v_mfma_f32_16x16x32_bf16 v[42:45], v[142:145], v[188:191], v[42:45]
	v_mfma_f32_16x16x32_bf16 v[42:45], v[146:149], v[192:195], v[42:45]
	v_mfma_f32_16x16x32_bf16 v[26:29], v[142:145], v[202:205], v[26:29]
	v_mfma_f32_16x16x32_bf16 v[26:29], v[146:149], v[206:209], v[26:29]
	v_mfma_f32_16x16x32_bf16 v[10:13], v[142:145], v[210:213], v[10:13]
	v_mfma_f32_16x16x32_bf16 v[10:13], v[146:149], v[214:217], v[10:13]
	v_mfma_f32_16x16x32_bf16 v[62:65], v[150:153], v[180:183], v[62:65]
	v_mfma_f32_16x16x32_bf16 v[62:65], v[154:157], v[184:187], v[62:65]
	v_mfma_f32_16x16x32_bf16 v[46:49], v[150:153], v[188:191], v[46:49]
	v_mfma_f32_16x16x32_bf16 v[46:49], v[154:157], v[192:195], v[46:49]
	v_mfma_f32_16x16x32_bf16 v[30:33], v[150:153], v[202:205], v[30:33]
	v_mfma_f32_16x16x32_bf16 v[30:33], v[154:157], v[206:209], v[30:33]
	v_mfma_f32_16x16x32_bf16 v[14:17], v[150:153], v[210:213], v[14:17]
	v_mfma_f32_16x16x32_bf16 v[14:17], v[154:157], v[214:217], v[14:17]
	s_setprio 0
	s_barrier
	s_add_i32 s84, s84, 2
	s_add_u32 s48, s48, 0x100
	s_addc_u32 s49, s49, 0
	s_add_u32 s53, s53, 0x100
	s_addc_u32 s69, s69, 0
	s_cmp_gt_u32 s84, 13
	s_cbranch_scc0 .LBB0_408
	s_and_b64 vcc, exec, s[64:65]
	s_cbranch_vccz .LBB0_411
	s_barrier
